# gu supertile: prefetch next round prologue before epilogue
# baseline (speedup 1.0000x reference)
; #define MFMA(a, b, c) __builtin_amdgcn_mfma_f32_32x32x16_bf16((a), (b), (c), 0, 0, 0)
; #define TIDX opaque_tid()
; template <int AI, int BI>
; DI void gemm_tile(const u16* __restrict__ A, int lda, const u16* __restrict__ B, int ldb, int nk, bool swap,
;                   f32x16 (&acc)[AI][BI], char* lds) {
;   const int tid = TIDX, lane = tid & 63, wid = tid >> 6;
;   gemm_stage<AI, BI>(A, lda, B, ldb, lds, tid);
;   asm volatile("s_waitcnt vmcnt(0)" ::: "memory");
;   __syncthreads();
;   const int wa = wid >> 1, wb = wid & 1, r = lane & 31, h = lane >> 5, sw = (r >> 1) & 7;
;   const int offA = (swap ? 16384 : 0) + (wa * 32 * AI + r) * 128;
;   const int offB = (swap ? 0 : 16384) + (wb * 32 * BI + r) * 128;
;   for (int kt = 0; kt < nk; ++kt) {
;     const char* cur = lds + (kt & 1) * 32768;
;     if (kt + 1 < nk) gemm_stage<AI, BI>(A + (kt + 1) * 64, lda, B + (kt + 1) * 64, ldb, lds + ((kt + 1) & 1) * 32768, tid);
; #pragma unroll
;     for (int ks = 0; ks < 4; ++ks) {
;       const int co = ((ks * 2 + h) ^ sw) << 4;
;       s16x8 fa[AI], fb[BI];
; #pragma unroll
;       for (int i = 0; i < AI; ++i) fa[i] = *(const s16x8*)(cur + offA + i * 4096 + co);
; #pragma unroll
;       for (int i = 0; i < BI; ++i) fb[i] = *(const s16x8*)(cur + offB + i * 4096 + co);
; #pragma unroll
;       for (int i = 0; i < AI; ++i)
; #pragma unroll
;         for (int j = 0; j < BI; ++j) acc[i][j] = MFMA(fa[i], fb[j], acc[i][j]);
;     }
; template <int AI>
; DI void gu_tile(char* wsb, int sub, int m0, int n0, char* lds) {
;   const u16* H = (const u16*)(wsb + OFF_H);
;   const u16* W = (const u16*)(wsb + OFF_W) + (sub ? W_GU1 : W_GU0);
;   u16* HID = (u16*)(wsb + OFF_HID);
;   const int lane = TIDX & 63, wid = TIDX >> 6, wa = wid >> 1, wb = wid & 1, r = lane & 31, h = lane >> 5;
;   f32x16 acc[AI][2]; zero_acc<AI, 2>(acc);
;   gemm_tile<AI, 2>(H + (size_t)m0 * 1024, 1024, W + (size_t)n0 * 1024, 1024, 16, false, acc, lds);
.LBB0_417:
	s_or_b64 exec, exec, s[6:7]
	s_mov_b32 s6, s19
	s_mov_b64 s[8:9], s[20:21]
	s_waitcnt lgkmcnt(0)
	s_barrier
	s_mov_b64 s[14:15], s[26:27]
	s_add_u32 s8, s14, s6
	v_readlane_b32 s6, v244, 48
	v_readlane_b32 s7, v244, 49
	s_mov_b64 s[10:11], s[22:23]
	s_addc_u32 s9, s15, 0
	v_cndmask_b32_e64 v0, 0, 1, s[6:7]
	v_cmp_ne_u32_e64 s[10:11], 1, v0
	s_andn2_b64 vcc, exec, s[6:7]
	s_mov_b64 s[12:13], s[24:25]
	v_writelane_b32 v242, s10, 3
	s_nop 1
	v_writelane_b32 v242, s11, 4
	s_cbranch_vccnz .LBB0_421
	s_add_u32 s10, s8, 0x77b7000
	s_addc_u32 s11, s9, 0
	s_add_u32 s12, s8, 0x1c4b7000
	s_addc_u32 s13, s9, 0
	s_add_u32 s6, s8, 0x9bb7000
	s_addc_u32 s7, s9, 0
	v_readlane_b32 s14, v243, 18
	v_readlane_b32 s15, v243, 5
	v_readlane_b32 s53, v243, 7
	s_mov_b32 s54, 0x1ffffc0
	s_mov_b64 s[70:71], 0x300
	s_mov_b64 s[72:73], 0x380
	s_mov_b64 s[74:75], 0x400
	s_mov_b64 s[76:77], 0x480
	s_mov_b64 s[80:81], 0x500
	s_mov_b64 s[82:83], 0x580
	s_mov_b64 s[84:85], 0x600
	s_mov_b64 s[56:57], 0x200
	s_mov_b64 s[64:65], 0x80
	s_mov_b64 s[66:67], 0x180
	s_mov_b64 s[68:69], 0x280
	s_cmpk_lg_u32 s92, 0x200
	s_cbranch_scc1 .LBB0_419
	v_and_b32_e32 v0, 31, v178
	v_bfe_u32 v122, v178, 5, 1
	v_bfe_u32 v123, v178, 2, 2
	v_xor_b32_e32 v122, v122, v123
	v_lshlrev_b32_e32 v122, 4, v122
	v_bfe_u32 v123, v178, 7, 1
	v_lshl_add_u32 v123, v123, 6, v0
	v_lshl_add_u32 v142, v123, 6, v122
	v_xor_b32_e32 v143, 32, v142
	v_bfe_u32 v123, v178, 6, 1
	v_lshl_add_u32 v123, v123, 6, v0
	v_lshl_add_u32 v144, v123, 6, v122
	v_add_u32_e32 v144, 0xc000, v144
	v_xor_b32_e32 v145, 32, v144
	v_bfe_u32 v122, v178, 7, 1
	v_lshlrev_b32_e32 v122, 6, v122
	v_bfe_u32 v123, v178, 5, 1
	v_lshl_add_u32 v122, v123, 2, v122
	v_mul_u32_u24_e32 v122, 0xb00, v122
	v_bfe_u32 v123, v178, 6, 1
	v_lshl_add_u32 v123, v123, 5, v0
	v_add_u32_e32 v122, v122, v123
	v_lshlrev_b32_e32 v124, 1, v122
	v_lshrrev_b32_e32 v0, 2, v178
	v_bfe_u32 v122, v178, 4, 2
	v_and_b32_e32 v123, 3, v178
	v_xor_b32_e32 v122, v122, v123
	v_lshlrev_b32_e32 v122, 4, v122
	v_lshl_add_u32 v126, v0, 11, v122
	v_add_u32_e32 v127, 0x20000, v126
	v_add_u32_e32 v128, 0x40000, v126
	v_add_u32_e32 v129, 0x60000, v126
	v_lshrrev_b32_e32 v0, 6, v178
	s_nop 1
	v_readfirstlane_b32 s18, v0
	s_lshl_b32 s18, s18, 10
	s_and_b32 s41, s96, 7
	s_lshr_b32 s40, s96, 3
	s_mov_b32 s32, 0
	s_lshr_b32 s37, s40, 3
	s_lshl_b32 s50, s32, 3
	s_add_u32 s37, s37, s50
	s_and_b32 s50, s40, 7
	s_lshl_b32 s51, s41, 3
	s_add_u32 s50, s50, s51
	s_lshl_b32 s51, s50, 19
	s_add_u32 s16, s10, s51
	s_addc_u32 s17, s11, 0
	s_lshl_b32 s51, s37, 18
	s_add_u32 s28, s12, s51
	s_addc_u32 s29, s13, 0
	s_lshr_b32 s37, s40, 3
	s_lshl_b32 s50, s32, 3
	s_add_u32 s37, s37, s50
	s_and_b32 s50, s40, 7
	s_lshl_b32 s51, s41, 3
	s_add_u32 s50, s50, s51
	s_mul_i32 s51, s50, 0x160000
	s_lshl_b32 s52, s37, 7
	s_add_u32 s51, s51, s52
	s_add_u32 s34, s6, s51
	s_addc_u32 s35, s7, 0
	s_add_u32 m0, s18, 0
	s_nop 0
	global_load_lds_dwordx4 v126, s[16:17]
	s_add_u32 m0, s18, 4096
	s_nop 0
	global_load_lds_dwordx4 v127, s[16:17]
	s_add_u32 m0, s18, 8192
	s_nop 0
	global_load_lds_dwordx4 v128, s[16:17]
	s_add_u32 m0, s18, 12288
	s_nop 0
	global_load_lds_dwordx4 v129, s[16:17]
	s_add_u32 m0, s18, 49152
	s_nop 0
	global_load_lds_dwordx4 v126, s[28:29]
	s_add_u32 m0, s18, 53248
	s_nop 0
	global_load_lds_dwordx4 v127, s[28:29]
	s_add_u32 s16, s16, 64
	s_addc_u32 s17, s17, 0
	s_add_u32 s28, s28, 64
	s_addc_u32 s29, s29, 0
	s_add_u32 m0, s18, 16384
	s_nop 0
	global_load_lds_dwordx4 v126, s[16:17]
	s_add_u32 m0, s18, 20480
	s_nop 0
	global_load_lds_dwordx4 v127, s[16:17]
	s_add_u32 m0, s18, 24576
	s_nop 0
	global_load_lds_dwordx4 v128, s[16:17]
	s_add_u32 m0, s18, 28672
	s_nop 0
	global_load_lds_dwordx4 v129, s[16:17]
	s_add_u32 m0, s18, 57344
	s_nop 0
	global_load_lds_dwordx4 v126, s[28:29]
	s_add_u32 m0, s18, 61440
	s_nop 0
	global_load_lds_dwordx4 v127, s[28:29]
	s_add_u32 s16, s16, 64
	s_addc_u32 s17, s17, 0
	s_add_u32 s28, s28, 64
	s_addc_u32 s29, s29, 0
	s_waitcnt vmcnt(6)
	s_barrier
	ds_read_b128 v[114:117], v142 offset:0
	ds_read_b128 v[230:233], v144 offset:0
	ds_read_b128 v[234:237], v144 offset:2048
	ds_read_b128 v[118:121], v142 offset:2048
	ds_read_b128 v[134:137], v142 offset:8192
	ds_read_b128 v[138:141], v142 offset:10240
	ds_read_b128 v[238:241], v145 offset:0
	ds_read_b128 v[246:249], v145 offset:2048
	s_add_u32 m0, s18, 32768
	s_nop 0
	global_load_lds_dwordx4 v126, s[16:17]
	s_add_u32 m0, s18, 36864
	s_nop 0
	global_load_lds_dwordx4 v127, s[16:17]
	s_add_u32 m0, s18, 40960
	s_nop 0
	global_load_lds_dwordx4 v128, s[16:17]
	s_add_u32 m0, s18, 45056
	s_nop 0
	global_load_lds_dwordx4 v129, s[16:17]
	s_add_u32 m0, s18, 65664
	s_nop 0
	global_load_lds_dwordx4 v126, s[28:29]
	s_add_u32 m0, s18, 69760
	s_nop 0
	global_load_lds_dwordx4 v127, s[28:29]
	s_add_u32 s16, s16, 64
	s_addc_u32 s17, s17, 0
	s_add_u32 s28, s28, 64
	s_addc_u32 s29, s29, 0
	s_waitcnt lgkmcnt(6)
	v_mfma_f32_32x32x16_bf16 v[2:17], v[114:117], v[230:233], 0
	s_waitcnt lgkmcnt(5)
	v_mfma_f32_32x32x16_bf16 v[18:33], v[114:117], v[234:237], 0
	ds_read_b128 v[114:117], v143 offset:0
	s_waitcnt lgkmcnt(5)
	v_mfma_f32_32x32x16_bf16 v[34:49], v[118:121], v[230:233], 0
	v_mfma_f32_32x32x16_bf16 v[50:65], v[118:121], v[234:237], 0
	ds_read_b128 v[118:121], v143 offset:2048
	s_waitcnt lgkmcnt(5)
	v_mfma_f32_32x32x16_bf16 v[66:81], v[134:137], v[230:233], 0
	v_mfma_f32_32x32x16_bf16 v[82:97], v[134:137], v[234:237], 0
	ds_read_b128 v[134:137], v143 offset:8192
	s_waitcnt lgkmcnt(5)
	v_mfma_f32_32x32x16_bf16 v[98:113], v[138:141], v[230:233], 0
	v_mfma_f32_32x32x16_bf16 v[214:229], v[138:141], v[234:237], 0
	ds_read_b128 v[138:141], v143 offset:10240
	s_waitcnt lgkmcnt(3)
	v_mfma_f32_32x32x16_bf16 v[2:17], v[114:117], v[238:241], v[2:17]
	v_mfma_f32_32x32x16_bf16 v[18:33], v[114:117], v[246:249], v[18:33]
	s_waitcnt lgkmcnt(2)
	v_mfma_f32_32x32x16_bf16 v[34:49], v[118:121], v[238:241], v[34:49]
	v_mfma_f32_32x32x16_bf16 v[50:65], v[118:121], v[246:249], v[50:65]
	s_waitcnt lgkmcnt(1)
	v_mfma_f32_32x32x16_bf16 v[66:81], v[134:137], v[238:241], v[66:81]
	v_mfma_f32_32x32x16_bf16 v[82:97], v[134:137], v[246:249], v[82:97]
	s_waitcnt lgkmcnt(0)
	v_mfma_f32_32x32x16_bf16 v[98:113], v[138:141], v[238:241], v[98:113]
	v_mfma_f32_32x32x16_bf16 v[214:229], v[138:141], v[246:249], v[214:229]
	s_waitcnt vmcnt(6)
	s_barrier
; #define MFMA(a, b, c) __builtin_amdgcn_mfma_f32_32x32x16_bf16((a), (b), (c), 0, 0, 0)
; template <int AI, int BI>
; DI void gemm_tile(const u16* __restrict__ A, int lda, const u16* __restrict__ B, int ldb, int nk, bool swap,
;                   f32x16 (&acc)[AI][BI], char* lds) {
;     ...
;   for (int kt = 0; kt < nk; ++kt) {
;     const char* cur = lds + (kt & 1) * 32768;
;     if (kt + 1 < nk) gemm_stage<AI, BI>(A + (kt + 1) * 64, lda, B + (kt + 1) * 64, ldb, lds + ((kt + 1) & 1) * 32768, tid);
; #pragma unroll
;     for (int ks = 0; ks < 4; ++ks) {
;       const int co = ((ks * 2 + h) ^ sw) << 4;
;       s16x8 fa[AI], fb[BI];
; #pragma unroll
;       for (int i = 0; i < AI; ++i) fa[i] = *(const s16x8*)(cur + offA + i * 4096 + co);
; #pragma unroll
;       for (int i = 0; i < BI; ++i) fb[i] = *(const s16x8*)(cur + offB + i * 4096 + co);
; #pragma unroll
;       for (int i = 0; i < AI; ++i)
; #pragma unroll
;         for (int j = 0; j < BI; ++j) acc[i][j] = MFMA(fa[i], fb[j], acc[i][j]);
;     }
	ds_read_b128 v[114:117], v142 offset:16384
	ds_read_b128 v[230:233], v144 offset:8192
	ds_read_b128 v[234:237], v144 offset:10240
	ds_read_b128 v[118:121], v142 offset:18432
	ds_read_b128 v[134:137], v142 offset:24576
	ds_read_b128 v[138:141], v142 offset:26624
	ds_read_b128 v[238:241], v145 offset:8192
	ds_read_b128 v[246:249], v145 offset:10240
	s_add_u32 m0, s18, 0
	s_nop 0
	global_load_lds_dwordx4 v126, s[16:17]
	s_add_u32 m0, s18, 4096
	s_nop 0
	global_load_lds_dwordx4 v127, s[16:17]
	s_add_u32 m0, s18, 8192
	s_nop 0
	global_load_lds_dwordx4 v128, s[16:17]
	s_add_u32 m0, s18, 12288
	s_nop 0
	global_load_lds_dwordx4 v129, s[16:17]
	s_add_u32 m0, s18, 49152
	s_nop 0
	global_load_lds_dwordx4 v126, s[28:29]
	s_add_u32 m0, s18, 53248
	s_nop 0
	global_load_lds_dwordx4 v127, s[28:29]
	s_add_u32 s16, s16, 64
	s_addc_u32 s17, s17, 0
	s_add_u32 s28, s28, 64
	s_addc_u32 s29, s29, 0
	s_waitcnt lgkmcnt(6)
	v_mfma_f32_32x32x16_bf16 v[2:17], v[114:117], v[230:233], v[2:17]
	s_waitcnt lgkmcnt(5)
	v_mfma_f32_32x32x16_bf16 v[18:33], v[114:117], v[234:237], v[18:33]
	ds_read_b128 v[114:117], v143 offset:16384
	s_waitcnt lgkmcnt(5)
	v_mfma_f32_32x32x16_bf16 v[34:49], v[118:121], v[230:233], v[34:49]
	v_mfma_f32_32x32x16_bf16 v[50:65], v[118:121], v[234:237], v[50:65]
	ds_read_b128 v[118:121], v143 offset:18432
	s_waitcnt lgkmcnt(5)
	v_mfma_f32_32x32x16_bf16 v[66:81], v[134:137], v[230:233], v[66:81]
	v_mfma_f32_32x32x16_bf16 v[82:97], v[134:137], v[234:237], v[82:97]
	ds_read_b128 v[134:137], v143 offset:24576
	s_waitcnt lgkmcnt(5)
	v_mfma_f32_32x32x16_bf16 v[98:113], v[138:141], v[230:233], v[98:113]
	v_mfma_f32_32x32x16_bf16 v[214:229], v[138:141], v[234:237], v[214:229]
	ds_read_b128 v[138:141], v143 offset:26624
	s_waitcnt lgkmcnt(3)
	v_mfma_f32_32x32x16_bf16 v[2:17], v[114:117], v[238:241], v[2:17]
	v_mfma_f32_32x32x16_bf16 v[18:33], v[114:117], v[246:249], v[18:33]
	s_waitcnt lgkmcnt(2)
	v_mfma_f32_32x32x16_bf16 v[34:49], v[118:121], v[238:241], v[34:49]
	v_mfma_f32_32x32x16_bf16 v[50:65], v[118:121], v[246:249], v[50:65]
	s_waitcnt lgkmcnt(1)
	v_mfma_f32_32x32x16_bf16 v[66:81], v[134:137], v[238:241], v[66:81]
	v_mfma_f32_32x32x16_bf16 v[82:97], v[134:137], v[246:249], v[82:97]
	s_waitcnt lgkmcnt(0)
	v_mfma_f32_32x32x16_bf16 v[98:113], v[138:141], v[238:241], v[98:113]
	v_mfma_f32_32x32x16_bf16 v[214:229], v[138:141], v[246:249], v[214:229]
	s_waitcnt vmcnt(6)
	s_barrier
	ds_read_b128 v[114:117], v142 offset:32768
	ds_read_b128 v[230:233], v144 offset:16512
	ds_read_b128 v[234:237], v144 offset:18560
	ds_read_b128 v[118:121], v142 offset:34816
	ds_read_b128 v[134:137], v142 offset:40960
	ds_read_b128 v[138:141], v142 offset:43008
	ds_read_b128 v[238:241], v145 offset:16512
	ds_read_b128 v[246:249], v145 offset:18560
	s_add_u32 m0, s18, 16384
	s_nop 0
	global_load_lds_dwordx4 v126, s[16:17]
	s_add_u32 m0, s18, 20480
	s_nop 0
	global_load_lds_dwordx4 v127, s[16:17]
	s_add_u32 m0, s18, 24576
	s_nop 0
	global_load_lds_dwordx4 v128, s[16:17]
	s_add_u32 m0, s18, 28672
	s_nop 0
	global_load_lds_dwordx4 v129, s[16:17]
	s_add_u32 m0, s18, 57344
	s_nop 0
	global_load_lds_dwordx4 v126, s[28:29]
	s_add_u32 m0, s18, 61440
	s_nop 0
	global_load_lds_dwordx4 v127, s[28:29]
	s_add_u32 s16, s16, 64
	s_addc_u32 s17, s17, 0
	s_add_u32 s28, s28, 64
	s_addc_u32 s29, s29, 0
	s_waitcnt lgkmcnt(6)
	v_mfma_f32_32x32x16_bf16 v[2:17], v[114:117], v[230:233], v[2:17]
	s_waitcnt lgkmcnt(5)
	v_mfma_f32_32x32x16_bf16 v[18:33], v[114:117], v[234:237], v[18:33]
	ds_read_b128 v[114:117], v143 offset:32768
	s_waitcnt lgkmcnt(5)
	v_mfma_f32_32x32x16_bf16 v[34:49], v[118:121], v[230:233], v[34:49]
	v_mfma_f32_32x32x16_bf16 v[50:65], v[118:121], v[234:237], v[50:65]
	ds_read_b128 v[118:121], v143 offset:34816
	s_waitcnt lgkmcnt(5)
	v_mfma_f32_32x32x16_bf16 v[66:81], v[134:137], v[230:233], v[66:81]
	v_mfma_f32_32x32x16_bf16 v[82:97], v[134:137], v[234:237], v[82:97]
	ds_read_b128 v[134:137], v143 offset:40960
	s_waitcnt lgkmcnt(5)
	v_mfma_f32_32x32x16_bf16 v[98:113], v[138:141], v[230:233], v[98:113]
	v_mfma_f32_32x32x16_bf16 v[214:229], v[138:141], v[234:237], v[214:229]
	ds_read_b128 v[138:141], v143 offset:43008
	s_waitcnt lgkmcnt(3)
	v_mfma_f32_32x32x16_bf16 v[2:17], v[114:117], v[238:241], v[2:17]
	v_mfma_f32_32x32x16_bf16 v[18:33], v[114:117], v[246:249], v[18:33]
	s_waitcnt lgkmcnt(2)
	v_mfma_f32_32x32x16_bf16 v[34:49], v[118:121], v[238:241], v[34:49]
	v_mfma_f32_32x32x16_bf16 v[50:65], v[118:121], v[246:249], v[50:65]
	s_waitcnt lgkmcnt(1)
	v_mfma_f32_32x32x16_bf16 v[66:81], v[134:137], v[238:241], v[66:81]
	v_mfma_f32_32x32x16_bf16 v[82:97], v[134:137], v[246:249], v[82:97]
	s_waitcnt lgkmcnt(0)
	v_mfma_f32_32x32x16_bf16 v[98:113], v[138:141], v[238:241], v[98:113]
	v_mfma_f32_32x32x16_bf16 v[214:229], v[138:141], v[246:249], v[214:229]
	s_branch .Lgu1_common
; #define MFMA(a, b, c) __builtin_amdgcn_mfma_f32_32x32x16_bf16((a), (b), (c), 0, 0, 0)
; template <int AI, int BI>
; DI void gemm_tile(const u16* __restrict__ A, int lda, const u16* __restrict__ B, int ldb, int nk, bool swap,
;                   f32x16 (&acc)[AI][BI], char* lds) {
;     ...
;   for (int kt = 0; kt < nk; ++kt) {
;     const char* cur = lds + (kt & 1) * 32768;
;     if (kt + 1 < nk) gemm_stage<AI, BI>(A + (kt + 1) * 64, lda, B + (kt + 1) * 64, ldb, lds + ((kt + 1) & 1) * 32768, tid);
; #pragma unroll
;     for (int ks = 0; ks < 4; ++ks) {
;       const int co = ((ks * 2 + h) ^ sw) << 4;
;       s16x8 fa[AI], fb[BI];
; #pragma unroll
;       for (int i = 0; i < AI; ++i) fa[i] = *(const s16x8*)(cur + offA + i * 4096 + co);
; #pragma unroll
;       for (int i = 0; i < BI; ++i) fb[i] = *(const s16x8*)(cur + offB + i * 4096 + co);
; #pragma unroll
;       for (int i = 0; i < AI; ++i)
; #pragma unroll
;         for (int j = 0; j < BI; ++j) acc[i][j] = MFMA(fa[i], fb[j], acc[i][j]);
;     }
.Lgu1_round:
	s_waitcnt vmcnt(63)
	s_barrier
	ds_read_b128 v[114:117], v142 offset:0
	ds_read_b128 v[230:233], v144 offset:0
	ds_read_b128 v[234:237], v144 offset:2048
	ds_read_b128 v[118:121], v142 offset:2048
	ds_read_b128 v[134:137], v142 offset:8192
	ds_read_b128 v[138:141], v142 offset:10240
	ds_read_b128 v[238:241], v145 offset:0
	ds_read_b128 v[246:249], v145 offset:2048
	s_add_u32 m0, s18, 32768
	s_nop 0
	global_load_lds_dwordx4 v126, s[16:17]
	s_add_u32 m0, s18, 36864
	s_nop 0
	global_load_lds_dwordx4 v127, s[16:17]
	s_add_u32 m0, s18, 40960
	s_nop 0
	global_load_lds_dwordx4 v128, s[16:17]
	s_add_u32 m0, s18, 45056
	s_nop 0
	global_load_lds_dwordx4 v129, s[16:17]
	s_add_u32 m0, s18, 65664
	s_nop 0
	global_load_lds_dwordx4 v126, s[28:29]
	s_add_u32 m0, s18, 69760
	s_nop 0
	global_load_lds_dwordx4 v127, s[28:29]
	s_add_u32 s16, s16, 64
	s_addc_u32 s17, s17, 0
	s_add_u32 s28, s28, 64
	s_addc_u32 s29, s29, 0
	s_waitcnt lgkmcnt(6)
	v_mfma_f32_32x32x16_bf16 v[2:17], v[114:117], v[230:233], 0
	s_waitcnt lgkmcnt(5)
	v_mfma_f32_32x32x16_bf16 v[18:33], v[114:117], v[234:237], 0
	ds_read_b128 v[114:117], v143 offset:0
	s_waitcnt lgkmcnt(5)
	v_mfma_f32_32x32x16_bf16 v[34:49], v[118:121], v[230:233], 0
	v_mfma_f32_32x32x16_bf16 v[50:65], v[118:121], v[234:237], 0
	ds_read_b128 v[118:121], v143 offset:2048
	s_waitcnt lgkmcnt(5)
	v_mfma_f32_32x32x16_bf16 v[66:81], v[134:137], v[230:233], 0
	v_mfma_f32_32x32x16_bf16 v[82:97], v[134:137], v[234:237], 0
	ds_read_b128 v[134:137], v143 offset:8192
	s_waitcnt lgkmcnt(5)
	v_mfma_f32_32x32x16_bf16 v[98:113], v[138:141], v[230:233], 0
	v_mfma_f32_32x32x16_bf16 v[214:229], v[138:141], v[234:237], 0
	ds_read_b128 v[138:141], v143 offset:10240
	s_waitcnt lgkmcnt(3)
	v_mfma_f32_32x32x16_bf16 v[2:17], v[114:117], v[238:241], v[2:17]
	v_mfma_f32_32x32x16_bf16 v[18:33], v[114:117], v[246:249], v[18:33]
	s_waitcnt lgkmcnt(2)
	v_mfma_f32_32x32x16_bf16 v[34:49], v[118:121], v[238:241], v[34:49]
	v_mfma_f32_32x32x16_bf16 v[50:65], v[118:121], v[246:249], v[50:65]
	s_waitcnt lgkmcnt(1)
	v_mfma_f32_32x32x16_bf16 v[66:81], v[134:137], v[238:241], v[66:81]
	v_mfma_f32_32x32x16_bf16 v[82:97], v[134:137], v[246:249], v[82:97]
	s_waitcnt lgkmcnt(0)
	v_mfma_f32_32x32x16_bf16 v[98:113], v[138:141], v[238:241], v[98:113]
	v_mfma_f32_32x32x16_bf16 v[214:229], v[138:141], v[246:249], v[214:229]
	s_waitcnt vmcnt(63)
	s_barrier
	ds_read_b128 v[114:117], v142 offset:16384
	ds_read_b128 v[230:233], v144 offset:8192
	ds_read_b128 v[234:237], v144 offset:10240
	ds_read_b128 v[118:121], v142 offset:18432
	ds_read_b128 v[134:137], v142 offset:24576
	ds_read_b128 v[138:141], v142 offset:26624
	ds_read_b128 v[238:241], v145 offset:8192
	ds_read_b128 v[246:249], v145 offset:10240
	s_add_u32 m0, s18, 0
	s_nop 0
	global_load_lds_dwordx4 v126, s[16:17]
	s_add_u32 m0, s18, 4096
	s_nop 0
	global_load_lds_dwordx4 v127, s[16:17]
	s_add_u32 m0, s18, 8192
	s_nop 0
	global_load_lds_dwordx4 v128, s[16:17]
	s_add_u32 m0, s18, 12288
	s_nop 0
	global_load_lds_dwordx4 v129, s[16:17]
	s_add_u32 m0, s18, 49152
	s_nop 0
	global_load_lds_dwordx4 v126, s[28:29]
	s_add_u32 m0, s18, 53248
	s_nop 0
	global_load_lds_dwordx4 v127, s[28:29]
	s_add_u32 s16, s16, 64
	s_addc_u32 s17, s17, 0
	s_add_u32 s28, s28, 64
	s_addc_u32 s29, s29, 0
	s_waitcnt lgkmcnt(6)
	v_mfma_f32_32x32x16_bf16 v[2:17], v[114:117], v[230:233], v[2:17]
	s_waitcnt lgkmcnt(5)
	v_mfma_f32_32x32x16_bf16 v[18:33], v[114:117], v[234:237], v[18:33]
	ds_read_b128 v[114:117], v143 offset:16384
	s_waitcnt lgkmcnt(5)
	v_mfma_f32_32x32x16_bf16 v[34:49], v[118:121], v[230:233], v[34:49]
	v_mfma_f32_32x32x16_bf16 v[50:65], v[118:121], v[234:237], v[50:65]
	ds_read_b128 v[118:121], v143 offset:18432
	s_waitcnt lgkmcnt(5)
	v_mfma_f32_32x32x16_bf16 v[66:81], v[134:137], v[230:233], v[66:81]
	v_mfma_f32_32x32x16_bf16 v[82:97], v[134:137], v[234:237], v[82:97]
	ds_read_b128 v[134:137], v143 offset:24576
	s_waitcnt lgkmcnt(5)
	v_mfma_f32_32x32x16_bf16 v[98:113], v[138:141], v[230:233], v[98:113]
	v_mfma_f32_32x32x16_bf16 v[214:229], v[138:141], v[234:237], v[214:229]
	ds_read_b128 v[138:141], v143 offset:26624
	s_waitcnt lgkmcnt(3)
	v_mfma_f32_32x32x16_bf16 v[2:17], v[114:117], v[238:241], v[2:17]
	v_mfma_f32_32x32x16_bf16 v[18:33], v[114:117], v[246:249], v[18:33]
	s_waitcnt lgkmcnt(2)
	v_mfma_f32_32x32x16_bf16 v[34:49], v[118:121], v[238:241], v[34:49]
	v_mfma_f32_32x32x16_bf16 v[50:65], v[118:121], v[246:249], v[50:65]
	s_waitcnt lgkmcnt(1)
	v_mfma_f32_32x32x16_bf16 v[66:81], v[134:137], v[238:241], v[66:81]
	v_mfma_f32_32x32x16_bf16 v[82:97], v[134:137], v[246:249], v[82:97]
	s_waitcnt lgkmcnt(0)
	v_mfma_f32_32x32x16_bf16 v[98:113], v[138:141], v[238:241], v[98:113]
	v_mfma_f32_32x32x16_bf16 v[214:229], v[138:141], v[246:249], v[214:229]
	s_waitcnt vmcnt(6)
	s_barrier
; #define MFMA(a, b, c) __builtin_amdgcn_mfma_f32_32x32x16_bf16((a), (b), (c), 0, 0, 0)
; template <int AI, int BI>
; DI void gemm_tile(const u16* __restrict__ A, int lda, const u16* __restrict__ B, int ldb, int nk, bool swap,
;                   f32x16 (&acc)[AI][BI], char* lds) {
;     ...
;   for (int kt = 0; kt < nk; ++kt) {
;     const char* cur = lds + (kt & 1) * 32768;
;     if (kt + 1 < nk) gemm_stage<AI, BI>(A + (kt + 1) * 64, lda, B + (kt + 1) * 64, ldb, lds + ((kt + 1) & 1) * 32768, tid);
; #pragma unroll
;     for (int ks = 0; ks < 4; ++ks) {
;       const int co = ((ks * 2 + h) ^ sw) << 4;
;       s16x8 fa[AI], fb[BI];
; #pragma unroll
;       for (int i = 0; i < AI; ++i) fa[i] = *(const s16x8*)(cur + offA + i * 4096 + co);
; #pragma unroll
;       for (int i = 0; i < BI; ++i) fb[i] = *(const s16x8*)(cur + offB + i * 4096 + co);
; #pragma unroll
;       for (int i = 0; i < AI; ++i)
; #pragma unroll
;         for (int j = 0; j < BI; ++j) acc[i][j] = MFMA(fa[i], fb[j], acc[i][j]);
;     }
;     asm volatile("s_waitcnt vmcnt(0)" ::: "memory");
;     __syncthreads();
;   }
	ds_read_b128 v[114:117], v142 offset:32768
	ds_read_b128 v[230:233], v144 offset:16512
	ds_read_b128 v[234:237], v144 offset:18560
	ds_read_b128 v[118:121], v142 offset:34816
	ds_read_b128 v[134:137], v142 offset:40960
	ds_read_b128 v[138:141], v142 offset:43008
	ds_read_b128 v[238:241], v145 offset:16512
	ds_read_b128 v[246:249], v145 offset:18560
	s_add_u32 m0, s18, 16384
	s_nop 0
	global_load_lds_dwordx4 v126, s[16:17]
	s_add_u32 m0, s18, 20480
	s_nop 0
	global_load_lds_dwordx4 v127, s[16:17]
	s_add_u32 m0, s18, 24576
	s_nop 0
	global_load_lds_dwordx4 v128, s[16:17]
	s_add_u32 m0, s18, 28672
	s_nop 0
	global_load_lds_dwordx4 v129, s[16:17]
	s_add_u32 m0, s18, 57344
	s_nop 0
	global_load_lds_dwordx4 v126, s[28:29]
	s_add_u32 m0, s18, 61440
	s_nop 0
	global_load_lds_dwordx4 v127, s[28:29]
	s_add_u32 s16, s16, 64
	s_addc_u32 s17, s17, 0
	s_add_u32 s28, s28, 64
	s_addc_u32 s29, s29, 0
	s_waitcnt lgkmcnt(6)
	v_mfma_f32_32x32x16_bf16 v[2:17], v[114:117], v[230:233], v[2:17]
	s_waitcnt lgkmcnt(5)
	v_mfma_f32_32x32x16_bf16 v[18:33], v[114:117], v[234:237], v[18:33]
	ds_read_b128 v[114:117], v143 offset:32768
	s_waitcnt lgkmcnt(5)
	v_mfma_f32_32x32x16_bf16 v[34:49], v[118:121], v[230:233], v[34:49]
	v_mfma_f32_32x32x16_bf16 v[50:65], v[118:121], v[234:237], v[50:65]
	ds_read_b128 v[118:121], v143 offset:34816
	s_waitcnt lgkmcnt(5)
	v_mfma_f32_32x32x16_bf16 v[66:81], v[134:137], v[230:233], v[66:81]
	v_mfma_f32_32x32x16_bf16 v[82:97], v[134:137], v[234:237], v[82:97]
	ds_read_b128 v[134:137], v143 offset:40960
	s_waitcnt lgkmcnt(5)
	v_mfma_f32_32x32x16_bf16 v[98:113], v[138:141], v[230:233], v[98:113]
	v_mfma_f32_32x32x16_bf16 v[214:229], v[138:141], v[234:237], v[214:229]
	ds_read_b128 v[138:141], v143 offset:43008
	s_waitcnt lgkmcnt(3)
	v_mfma_f32_32x32x16_bf16 v[2:17], v[114:117], v[238:241], v[2:17]
	v_mfma_f32_32x32x16_bf16 v[18:33], v[114:117], v[246:249], v[18:33]
	s_waitcnt lgkmcnt(2)
	v_mfma_f32_32x32x16_bf16 v[34:49], v[118:121], v[238:241], v[34:49]
	v_mfma_f32_32x32x16_bf16 v[50:65], v[118:121], v[246:249], v[50:65]
	s_waitcnt lgkmcnt(1)
	v_mfma_f32_32x32x16_bf16 v[66:81], v[134:137], v[238:241], v[66:81]
	v_mfma_f32_32x32x16_bf16 v[82:97], v[134:137], v[246:249], v[82:97]
	s_waitcnt lgkmcnt(0)
	v_mfma_f32_32x32x16_bf16 v[98:113], v[138:141], v[238:241], v[98:113]
	v_mfma_f32_32x32x16_bf16 v[214:229], v[138:141], v[246:249], v[214:229]
.Lgu1_common:
	s_mov_b32 s36, 9
.Lgu1_kloop:
	s_waitcnt vmcnt(6)
	s_barrier
	ds_read_b128 v[114:117], v142 offset:0
	ds_read_b128 v[230:233], v144 offset:0
	ds_read_b128 v[234:237], v144 offset:2048
	ds_read_b128 v[118:121], v142 offset:2048
	ds_read_b128 v[134:137], v142 offset:8192
	ds_read_b128 v[138:141], v142 offset:10240
	ds_read_b128 v[238:241], v145 offset:0
	ds_read_b128 v[246:249], v145 offset:2048
	s_add_u32 m0, s18, 32768
	s_nop 0
	global_load_lds_dwordx4 v126, s[16:17]
	s_add_u32 m0, s18, 36864
	s_nop 0
	global_load_lds_dwordx4 v127, s[16:17]
	s_add_u32 m0, s18, 40960
	s_nop 0
	global_load_lds_dwordx4 v128, s[16:17]
	s_add_u32 m0, s18, 45056
	s_nop 0
	global_load_lds_dwordx4 v129, s[16:17]
	s_add_u32 m0, s18, 65664
	s_nop 0
	global_load_lds_dwordx4 v126, s[28:29]
	s_add_u32 m0, s18, 69760
	s_nop 0
	global_load_lds_dwordx4 v127, s[28:29]
	s_add_u32 s16, s16, 64
	s_addc_u32 s17, s17, 0
	s_add_u32 s28, s28, 64
	s_addc_u32 s29, s29, 0
	s_waitcnt lgkmcnt(6)
	v_mfma_f32_32x32x16_bf16 v[2:17], v[114:117], v[230:233], v[2:17]
	s_waitcnt lgkmcnt(5)
	v_mfma_f32_32x32x16_bf16 v[18:33], v[114:117], v[234:237], v[18:33]
	ds_read_b128 v[114:117], v143 offset:0
	s_waitcnt lgkmcnt(5)
	v_mfma_f32_32x32x16_bf16 v[34:49], v[118:121], v[230:233], v[34:49]
	v_mfma_f32_32x32x16_bf16 v[50:65], v[118:121], v[234:237], v[50:65]
	ds_read_b128 v[118:121], v143 offset:2048
	s_waitcnt lgkmcnt(5)
	v_mfma_f32_32x32x16_bf16 v[66:81], v[134:137], v[230:233], v[66:81]
	v_mfma_f32_32x32x16_bf16 v[82:97], v[134:137], v[234:237], v[82:97]
	ds_read_b128 v[134:137], v143 offset:8192
	s_waitcnt lgkmcnt(5)
	v_mfma_f32_32x32x16_bf16 v[98:113], v[138:141], v[230:233], v[98:113]
	v_mfma_f32_32x32x16_bf16 v[214:229], v[138:141], v[234:237], v[214:229]
	ds_read_b128 v[138:141], v143 offset:10240
	s_waitcnt lgkmcnt(3)
	v_mfma_f32_32x32x16_bf16 v[2:17], v[114:117], v[238:241], v[2:17]
	v_mfma_f32_32x32x16_bf16 v[18:33], v[114:117], v[246:249], v[18:33]
	s_waitcnt lgkmcnt(2)
	v_mfma_f32_32x32x16_bf16 v[34:49], v[118:121], v[238:241], v[34:49]
	v_mfma_f32_32x32x16_bf16 v[50:65], v[118:121], v[246:249], v[50:65]
	s_waitcnt lgkmcnt(1)
	v_mfma_f32_32x32x16_bf16 v[66:81], v[134:137], v[238:241], v[66:81]
	v_mfma_f32_32x32x16_bf16 v[82:97], v[134:137], v[246:249], v[82:97]
	s_waitcnt lgkmcnt(0)
	v_mfma_f32_32x32x16_bf16 v[98:113], v[138:141], v[238:241], v[98:113]
	v_mfma_f32_32x32x16_bf16 v[214:229], v[138:141], v[246:249], v[214:229]
	s_waitcnt vmcnt(6)
	s_barrier
; #define MFMA(a, b, c) __builtin_amdgcn_mfma_f32_32x32x16_bf16((a), (b), (c), 0, 0, 0)
; template <int AI, int BI>
; DI void gemm_tile(const u16* __restrict__ A, int lda, const u16* __restrict__ B, int ldb, int nk, bool swap,
;                   f32x16 (&acc)[AI][BI], char* lds) {
;     ...
;   for (int kt = 0; kt < nk; ++kt) {
;     const char* cur = lds + (kt & 1) * 32768;
;     if (kt + 1 < nk) gemm_stage<AI, BI>(A + (kt + 1) * 64, lda, B + (kt + 1) * 64, ldb, lds + ((kt + 1) & 1) * 32768, tid);
; #pragma unroll
;     for (int ks = 0; ks < 4; ++ks) {
;       const int co = ((ks * 2 + h) ^ sw) << 4;
;       s16x8 fa[AI], fb[BI];
; #pragma unroll
;       for (int i = 0; i < AI; ++i) fa[i] = *(const s16x8*)(cur + offA + i * 4096 + co);
; #pragma unroll
;       for (int i = 0; i < BI; ++i) fb[i] = *(const s16x8*)(cur + offB + i * 4096 + co);
; #pragma unroll
;       for (int i = 0; i < AI; ++i)
; #pragma unroll
;         for (int j = 0; j < BI; ++j) acc[i][j] = MFMA(fa[i], fb[j], acc[i][j]);
;     }
;     asm volatile("s_waitcnt vmcnt(0)" ::: "memory");
;     __syncthreads();
;   }
	ds_read_b128 v[114:117], v142 offset:16384
	ds_read_b128 v[230:233], v144 offset:8192
	ds_read_b128 v[234:237], v144 offset:10240
	ds_read_b128 v[118:121], v142 offset:18432
	ds_read_b128 v[134:137], v142 offset:24576
	ds_read_b128 v[138:141], v142 offset:26624
	ds_read_b128 v[238:241], v145 offset:8192
	ds_read_b128 v[246:249], v145 offset:10240
	s_add_u32 m0, s18, 0
	s_nop 0
	global_load_lds_dwordx4 v126, s[16:17]
	s_add_u32 m0, s18, 4096
	s_nop 0
	global_load_lds_dwordx4 v127, s[16:17]
	s_add_u32 m0, s18, 8192
	s_nop 0
	global_load_lds_dwordx4 v128, s[16:17]
	s_add_u32 m0, s18, 12288
	s_nop 0
	global_load_lds_dwordx4 v129, s[16:17]
	s_add_u32 m0, s18, 49152
	s_nop 0
	global_load_lds_dwordx4 v126, s[28:29]
	s_add_u32 m0, s18, 53248
	s_nop 0
	global_load_lds_dwordx4 v127, s[28:29]
	s_add_u32 s16, s16, 64
	s_addc_u32 s17, s17, 0
	s_add_u32 s28, s28, 64
	s_addc_u32 s29, s29, 0
	s_waitcnt lgkmcnt(6)
	v_mfma_f32_32x32x16_bf16 v[2:17], v[114:117], v[230:233], v[2:17]
	s_waitcnt lgkmcnt(5)
	v_mfma_f32_32x32x16_bf16 v[18:33], v[114:117], v[234:237], v[18:33]
	ds_read_b128 v[114:117], v143 offset:16384
	s_waitcnt lgkmcnt(5)
	v_mfma_f32_32x32x16_bf16 v[34:49], v[118:121], v[230:233], v[34:49]
	v_mfma_f32_32x32x16_bf16 v[50:65], v[118:121], v[234:237], v[50:65]
	ds_read_b128 v[118:121], v143 offset:18432
	s_waitcnt lgkmcnt(5)
	v_mfma_f32_32x32x16_bf16 v[66:81], v[134:137], v[230:233], v[66:81]
	v_mfma_f32_32x32x16_bf16 v[82:97], v[134:137], v[234:237], v[82:97]
	ds_read_b128 v[134:137], v143 offset:24576
	s_waitcnt lgkmcnt(5)
	v_mfma_f32_32x32x16_bf16 v[98:113], v[138:141], v[230:233], v[98:113]
	v_mfma_f32_32x32x16_bf16 v[214:229], v[138:141], v[234:237], v[214:229]
	ds_read_b128 v[138:141], v143 offset:26624
	s_waitcnt lgkmcnt(3)
	v_mfma_f32_32x32x16_bf16 v[2:17], v[114:117], v[238:241], v[2:17]
	v_mfma_f32_32x32x16_bf16 v[18:33], v[114:117], v[246:249], v[18:33]
	s_waitcnt lgkmcnt(2)
	v_mfma_f32_32x32x16_bf16 v[34:49], v[118:121], v[238:241], v[34:49]
	v_mfma_f32_32x32x16_bf16 v[50:65], v[118:121], v[246:249], v[50:65]
	s_waitcnt lgkmcnt(1)
	v_mfma_f32_32x32x16_bf16 v[66:81], v[134:137], v[238:241], v[66:81]
	v_mfma_f32_32x32x16_bf16 v[82:97], v[134:137], v[246:249], v[82:97]
	s_waitcnt lgkmcnt(0)
	v_mfma_f32_32x32x16_bf16 v[98:113], v[138:141], v[238:241], v[98:113]
	v_mfma_f32_32x32x16_bf16 v[214:229], v[138:141], v[246:249], v[214:229]
	s_waitcnt vmcnt(6)
	s_barrier
	ds_read_b128 v[114:117], v142 offset:32768
	ds_read_b128 v[230:233], v144 offset:16512
	ds_read_b128 v[234:237], v144 offset:18560
	ds_read_b128 v[118:121], v142 offset:34816
	ds_read_b128 v[134:137], v142 offset:40960
	ds_read_b128 v[138:141], v142 offset:43008
	ds_read_b128 v[238:241], v145 offset:16512
	ds_read_b128 v[246:249], v145 offset:18560
	s_add_u32 m0, s18, 16384
	s_nop 0
	global_load_lds_dwordx4 v126, s[16:17]
	s_add_u32 m0, s18, 20480
	s_nop 0
	global_load_lds_dwordx4 v127, s[16:17]
	s_add_u32 m0, s18, 24576
	s_nop 0
	global_load_lds_dwordx4 v128, s[16:17]
	s_add_u32 m0, s18, 28672
	s_nop 0
	global_load_lds_dwordx4 v129, s[16:17]
	s_add_u32 m0, s18, 57344
	s_nop 0
	global_load_lds_dwordx4 v126, s[28:29]
	s_add_u32 m0, s18, 61440
	s_nop 0
	global_load_lds_dwordx4 v127, s[28:29]
	s_add_u32 s16, s16, 64
	s_addc_u32 s17, s17, 0
	s_add_u32 s28, s28, 64
	s_addc_u32 s29, s29, 0
	s_waitcnt lgkmcnt(6)
	v_mfma_f32_32x32x16_bf16 v[2:17], v[114:117], v[230:233], v[2:17]
	s_waitcnt lgkmcnt(5)
	v_mfma_f32_32x32x16_bf16 v[18:33], v[114:117], v[234:237], v[18:33]
	ds_read_b128 v[114:117], v143 offset:32768
	s_waitcnt lgkmcnt(5)
	v_mfma_f32_32x32x16_bf16 v[34:49], v[118:121], v[230:233], v[34:49]
	v_mfma_f32_32x32x16_bf16 v[50:65], v[118:121], v[234:237], v[50:65]
	ds_read_b128 v[118:121], v143 offset:34816
	s_waitcnt lgkmcnt(5)
	v_mfma_f32_32x32x16_bf16 v[66:81], v[134:137], v[230:233], v[66:81]
	v_mfma_f32_32x32x16_bf16 v[82:97], v[134:137], v[234:237], v[82:97]
	ds_read_b128 v[134:137], v143 offset:40960
	s_waitcnt lgkmcnt(5)
	v_mfma_f32_32x32x16_bf16 v[98:113], v[138:141], v[230:233], v[98:113]
	v_mfma_f32_32x32x16_bf16 v[214:229], v[138:141], v[234:237], v[214:229]
	ds_read_b128 v[138:141], v143 offset:43008
	s_waitcnt lgkmcnt(3)
	v_mfma_f32_32x32x16_bf16 v[2:17], v[114:117], v[238:241], v[2:17]
	v_mfma_f32_32x32x16_bf16 v[18:33], v[114:117], v[246:249], v[18:33]
	s_waitcnt lgkmcnt(2)
	v_mfma_f32_32x32x16_bf16 v[34:49], v[118:121], v[238:241], v[34:49]
	v_mfma_f32_32x32x16_bf16 v[50:65], v[118:121], v[246:249], v[50:65]
	s_waitcnt lgkmcnt(1)
	v_mfma_f32_32x32x16_bf16 v[66:81], v[134:137], v[238:241], v[66:81]
	v_mfma_f32_32x32x16_bf16 v[82:97], v[134:137], v[246:249], v[82:97]
	s_waitcnt lgkmcnt(0)
	v_mfma_f32_32x32x16_bf16 v[98:113], v[138:141], v[238:241], v[98:113]
	v_mfma_f32_32x32x16_bf16 v[214:229], v[138:141], v[246:249], v[214:229]
	s_sub_u32 s36, s36, 1
	s_cmp_lg_u32 s36, 0
	s_cbranch_scc1 .Lgu1_kloop
	s_waitcnt vmcnt(6)
	s_barrier
; #define MFMA(a, b, c) __builtin_amdgcn_mfma_f32_32x32x16_bf16((a), (b), (c), 0, 0, 0)
; template <int AI, int BI>
; DI void gemm_tile(const u16* __restrict__ A, int lda, const u16* __restrict__ B, int ldb, int nk, bool swap,
;                   f32x16 (&acc)[AI][BI], char* lds) {
;     ...
;   for (int kt = 0; kt < nk; ++kt) {
;     const char* cur = lds + (kt & 1) * 32768;
;     if (kt + 1 < nk) gemm_stage<AI, BI>(A + (kt + 1) * 64, lda, B + (kt + 1) * 64, ldb, lds + ((kt + 1) & 1) * 32768, tid);
; #pragma unroll
;     for (int ks = 0; ks < 4; ++ks) {
;       const int co = ((ks * 2 + h) ^ sw) << 4;
;       s16x8 fa[AI], fb[BI];
; #pragma unroll
;       for (int i = 0; i < AI; ++i) fa[i] = *(const s16x8*)(cur + offA + i * 4096 + co);
; #pragma unroll
;       for (int i = 0; i < BI; ++i) fb[i] = *(const s16x8*)(cur + offB + i * 4096 + co);
; #pragma unroll
;       for (int i = 0; i < AI; ++i)
; #pragma unroll
;         for (int j = 0; j < BI; ++j) acc[i][j] = MFMA(fa[i], fb[j], acc[i][j]);
;     }
;     asm volatile("s_waitcnt vmcnt(0)" ::: "memory");
;     __syncthreads();
;   }
; DI void phase_gu(const Params& p, char* wsb, int sub, int mrows, char* lds) {
;   int mt, nt;
;   for (int rnd = 0; next_tile(rnd, 128, 44, mt, nt); ++rnd) gu_tile<2>(wsb, sub, mt * 128, nt * 128, lds);
	ds_read_b128 v[114:117], v142 offset:0
	ds_read_b128 v[230:233], v144 offset:0
	ds_read_b128 v[234:237], v144 offset:2048
	ds_read_b128 v[118:121], v142 offset:2048
	ds_read_b128 v[134:137], v142 offset:8192
	ds_read_b128 v[138:141], v142 offset:10240
	ds_read_b128 v[238:241], v145 offset:0
	ds_read_b128 v[246:249], v145 offset:2048
	s_waitcnt lgkmcnt(6)
	v_mfma_f32_32x32x16_bf16 v[2:17], v[114:117], v[230:233], v[2:17]
	s_waitcnt lgkmcnt(5)
	v_mfma_f32_32x32x16_bf16 v[18:33], v[114:117], v[234:237], v[18:33]
	ds_read_b128 v[114:117], v143 offset:0
	s_waitcnt lgkmcnt(5)
	v_mfma_f32_32x32x16_bf16 v[34:49], v[118:121], v[230:233], v[34:49]
	v_mfma_f32_32x32x16_bf16 v[50:65], v[118:121], v[234:237], v[50:65]
	ds_read_b128 v[118:121], v143 offset:2048
	s_waitcnt lgkmcnt(5)
	v_mfma_f32_32x32x16_bf16 v[66:81], v[134:137], v[230:233], v[66:81]
	v_mfma_f32_32x32x16_bf16 v[82:97], v[134:137], v[234:237], v[82:97]
	ds_read_b128 v[134:137], v143 offset:8192
	s_waitcnt lgkmcnt(5)
	v_mfma_f32_32x32x16_bf16 v[98:113], v[138:141], v[230:233], v[98:113]
	v_mfma_f32_32x32x16_bf16 v[214:229], v[138:141], v[234:237], v[214:229]
	ds_read_b128 v[138:141], v143 offset:10240
	s_waitcnt lgkmcnt(3)
	v_mfma_f32_32x32x16_bf16 v[2:17], v[114:117], v[238:241], v[2:17]
	v_mfma_f32_32x32x16_bf16 v[18:33], v[114:117], v[246:249], v[18:33]
	s_waitcnt lgkmcnt(2)
	v_mfma_f32_32x32x16_bf16 v[34:49], v[118:121], v[238:241], v[34:49]
	v_mfma_f32_32x32x16_bf16 v[50:65], v[118:121], v[246:249], v[50:65]
	s_waitcnt lgkmcnt(1)
	v_mfma_f32_32x32x16_bf16 v[66:81], v[134:137], v[238:241], v[66:81]
	v_mfma_f32_32x32x16_bf16 v[82:97], v[134:137], v[246:249], v[82:97]
	s_waitcnt lgkmcnt(0)
	v_mfma_f32_32x32x16_bf16 v[98:113], v[138:141], v[238:241], v[98:113]
	v_mfma_f32_32x32x16_bf16 v[214:229], v[138:141], v[246:249], v[214:229]
	s_waitcnt vmcnt(0)
	s_barrier
	ds_read_b128 v[114:117], v142 offset:16384
	ds_read_b128 v[230:233], v144 offset:8192
	ds_read_b128 v[234:237], v144 offset:10240
	ds_read_b128 v[118:121], v142 offset:18432
	ds_read_b128 v[134:137], v142 offset:24576
	ds_read_b128 v[138:141], v142 offset:26624
	ds_read_b128 v[238:241], v145 offset:8192
	ds_read_b128 v[246:249], v145 offset:10240
	s_waitcnt lgkmcnt(6)
	v_mfma_f32_32x32x16_bf16 v[2:17], v[114:117], v[230:233], v[2:17]
	s_waitcnt lgkmcnt(5)
	v_mfma_f32_32x32x16_bf16 v[18:33], v[114:117], v[234:237], v[18:33]
	ds_read_b128 v[114:117], v143 offset:16384
	s_waitcnt lgkmcnt(5)
	v_mfma_f32_32x32x16_bf16 v[34:49], v[118:121], v[230:233], v[34:49]
	v_mfma_f32_32x32x16_bf16 v[50:65], v[118:121], v[234:237], v[50:65]
	ds_read_b128 v[118:121], v143 offset:18432
	s_waitcnt lgkmcnt(5)
	v_mfma_f32_32x32x16_bf16 v[66:81], v[134:137], v[230:233], v[66:81]
	v_mfma_f32_32x32x16_bf16 v[82:97], v[134:137], v[234:237], v[82:97]
	ds_read_b128 v[134:137], v143 offset:24576
	s_waitcnt lgkmcnt(5)
	v_mfma_f32_32x32x16_bf16 v[98:113], v[138:141], v[230:233], v[98:113]
	v_mfma_f32_32x32x16_bf16 v[214:229], v[138:141], v[234:237], v[214:229]
	ds_read_b128 v[138:141], v143 offset:26624
	s_waitcnt lgkmcnt(3)
	v_mfma_f32_32x32x16_bf16 v[2:17], v[114:117], v[238:241], v[2:17]
	v_mfma_f32_32x32x16_bf16 v[18:33], v[114:117], v[246:249], v[18:33]
	s_waitcnt lgkmcnt(2)
	v_mfma_f32_32x32x16_bf16 v[34:49], v[118:121], v[238:241], v[34:49]
	v_mfma_f32_32x32x16_bf16 v[50:65], v[118:121], v[246:249], v[50:65]
	s_waitcnt lgkmcnt(1)
	v_mfma_f32_32x32x16_bf16 v[66:81], v[134:137], v[238:241], v[66:81]
	v_mfma_f32_32x32x16_bf16 v[82:97], v[134:137], v[246:249], v[82:97]
	s_waitcnt lgkmcnt(0)
	v_mfma_f32_32x32x16_bf16 v[98:113], v[138:141], v[238:241], v[98:113]
	v_mfma_f32_32x32x16_bf16 v[214:229], v[138:141], v[246:249], v[214:229]
	s_nop 7
	s_nop 7
	s_barrier
	s_add_u32 s32, s32, 1
	s_cmp_lt_u32 s32, 5
	s_cbranch_scc0 .Lgu1_nopf
	s_lshr_b32 s37, s40, 3
	s_lshl_b32 s50, s32, 3
	s_add_u32 s37, s37, s50
	s_and_b32 s50, s40, 7
	s_lshl_b32 s51, s41, 3
	s_add_u32 s50, s50, s51
	s_lshl_b32 s51, s50, 19
	s_add_u32 s16, s10, s51
	s_addc_u32 s17, s11, 0
	s_lshl_b32 s51, s37, 18
	s_add_u32 s28, s12, s51
	s_addc_u32 s29, s13, 0
	s_add_u32 m0, s18, 0
	s_nop 0
	global_load_lds_dwordx4 v126, s[16:17]
	s_add_u32 m0, s18, 4096
	s_nop 0
	global_load_lds_dwordx4 v127, s[16:17]
	s_add_u32 m0, s18, 8192
	s_nop 0
	global_load_lds_dwordx4 v128, s[16:17]
	s_add_u32 m0, s18, 12288
	s_nop 0
	global_load_lds_dwordx4 v129, s[16:17]
	s_add_u32 m0, s18, 49152
	s_nop 0
	global_load_lds_dwordx4 v126, s[28:29]
	s_add_u32 m0, s18, 53248
	s_nop 0
	global_load_lds_dwordx4 v127, s[28:29]
	s_add_u32 s16, s16, 64
	s_addc_u32 s17, s17, 0
	s_add_u32 s28, s28, 64
	s_addc_u32 s29, s29, 0
	s_add_u32 m0, s18, 16384
	s_nop 0
	global_load_lds_dwordx4 v126, s[16:17]
	s_add_u32 m0, s18, 20480
	s_nop 0
	global_load_lds_dwordx4 v127, s[16:17]
	s_add_u32 m0, s18, 24576
	s_nop 0
	global_load_lds_dwordx4 v128, s[16:17]
	s_add_u32 m0, s18, 28672
	s_nop 0
	global_load_lds_dwordx4 v129, s[16:17]
	s_add_u32 m0, s18, 57344
	s_nop 0
	global_load_lds_dwordx4 v126, s[28:29]
	s_add_u32 m0, s18, 61440
	s_nop 0
	global_load_lds_dwordx4 v127, s[28:29]
	s_add_u32 s16, s16, 64
	s_addc_u32 s17, s17, 0
	s_add_u32 s28, s28, 64
	s_addc_u32 s29, s29, 0
; #define GAS __attribute__((address_space(1)))
; DI int opaque0() { int z = 0; asm volatile("" : "+v"(z)); return z; }
; template <int AI>
; DI void gu_tile(char* wsb, int sub, int m0, int n0, char* lds) {
;     ...
;   const int m0e = m0 + opaque0();
;   const int hc = (n0 >> 1) + wb * 32 + r;
;   GAS u16* HIDu = uptr(HID);
;   const unsigned ib = (unsigned)((m0e + wa * 32 * AI + 4 * h) * 2816 + hc);
; #pragma unroll
;   for (int ai = 0; ai < AI; ++ai)
; #pragma unroll
;     for (int reg = 0; reg < 16; ++reg) {
;       float g = acc[ai][0][reg], u = acc[ai][1][reg];
;       float v = g * __builtin_amdgcn_rcpf(1.f + __expf(-g)) * u;
;       HIDu[ib + (unsigned)((ai * 32 + (reg & 3) + 8 * (reg >> 2)) * 2816)] = f2bf(v);
;       if ((reg & 7) == 7) __builtin_amdgcn_sched_barrier(0);
;     }
.Lgu1_nopf:
	v_mul_f32_e32 v250, 0xbfb8aa3b, v2
	v_mul_f32_e32 v252, 0xbfb8aa3b, v3
	v_exp_f32_e32 v250, v250
	v_exp_f32_e32 v252, v252
	v_add_u32_e32 v251, 0x0, v124
	v_add_f32_e32 v250, 1.0, v250
	v_add_f32_e32 v252, 1.0, v252
	v_rcp_f32_e32 v250, v250
	v_rcp_f32_e32 v252, v252
	v_add_u32_e32 v253, 0x1600, v124
	v_mul_f32_e32 v250, v2, v250
	v_mul_f32_e32 v252, v3, v252
	v_mul_f32_e32 v250, v18, v250
	v_mul_f32_e32 v252, v19, v252
	v_cvt_pk_bf16_f32 v250, v250, v250
	v_cvt_pk_bf16_f32 v252, v252, v252
	global_store_short v251, v250, s[34:35]
	global_store_short v253, v252, s[34:35]
	v_mul_f32_e32 v250, 0xbfb8aa3b, v4
	v_mul_f32_e32 v252, 0xbfb8aa3b, v5
	v_exp_f32_e32 v250, v250
	v_exp_f32_e32 v252, v252
	v_add_u32_e32 v251, 0x2c00, v124
	v_add_f32_e32 v250, 1.0, v250
	v_add_f32_e32 v252, 1.0, v252
	v_rcp_f32_e32 v250, v250
	v_rcp_f32_e32 v252, v252
	v_add_u32_e32 v253, 0x4200, v124
	v_mul_f32_e32 v250, v4, v250
	v_mul_f32_e32 v252, v5, v252
	v_mul_f32_e32 v250, v20, v250
	v_mul_f32_e32 v252, v21, v252
	v_cvt_pk_bf16_f32 v250, v250, v250
	v_cvt_pk_bf16_f32 v252, v252, v252
	global_store_short v251, v250, s[34:35]
	global_store_short v253, v252, s[34:35]
	v_mul_f32_e32 v250, 0xbfb8aa3b, v6
	v_mul_f32_e32 v252, 0xbfb8aa3b, v7
	v_exp_f32_e32 v250, v250
	v_exp_f32_e32 v252, v252
	v_add_u32_e32 v251, 0xb000, v124
	v_add_f32_e32 v250, 1.0, v250
	v_add_f32_e32 v252, 1.0, v252
	v_rcp_f32_e32 v250, v250
	v_rcp_f32_e32 v252, v252
	v_add_u32_e32 v253, 0xc600, v124
	v_mul_f32_e32 v250, v6, v250
	v_mul_f32_e32 v252, v7, v252
	v_mul_f32_e32 v250, v22, v250
	v_mul_f32_e32 v252, v23, v252
	v_cvt_pk_bf16_f32 v250, v250, v250
	v_cvt_pk_bf16_f32 v252, v252, v252
	global_store_short v251, v250, s[34:35]
	global_store_short v253, v252, s[34:35]
	v_mul_f32_e32 v250, 0xbfb8aa3b, v8
	v_mul_f32_e32 v252, 0xbfb8aa3b, v9
	v_exp_f32_e32 v250, v250
	v_exp_f32_e32 v252, v252
	v_add_u32_e32 v251, 0xdc00, v124
	v_add_f32_e32 v250, 1.0, v250
	v_add_f32_e32 v252, 1.0, v252
	v_rcp_f32_e32 v250, v250
	v_rcp_f32_e32 v252, v252
	v_add_u32_e32 v253, 0xf200, v124
	v_mul_f32_e32 v250, v8, v250
	v_mul_f32_e32 v252, v9, v252
	v_mul_f32_e32 v250, v24, v250
	v_mul_f32_e32 v252, v25, v252
	v_cvt_pk_bf16_f32 v250, v250, v250
	v_cvt_pk_bf16_f32 v252, v252, v252
	global_store_short v251, v250, s[34:35]
	global_store_short v253, v252, s[34:35]
	v_mul_f32_e32 v250, 0xbfb8aa3b, v10
	v_mul_f32_e32 v252, 0xbfb8aa3b, v11
	v_exp_f32_e32 v250, v250
	v_exp_f32_e32 v252, v252
	v_add_u32_e32 v251, 0x16000, v124
	v_add_f32_e32 v250, 1.0, v250
	v_add_f32_e32 v252, 1.0, v252
	v_rcp_f32_e32 v250, v250
	v_rcp_f32_e32 v252, v252
	v_add_u32_e32 v253, 0x17600, v124
	v_mul_f32_e32 v250, v10, v250
	v_mul_f32_e32 v252, v11, v252
	v_mul_f32_e32 v250, v26, v250
	v_mul_f32_e32 v252, v27, v252
	v_cvt_pk_bf16_f32 v250, v250, v250
	v_cvt_pk_bf16_f32 v252, v252, v252
	global_store_short v251, v250, s[34:35]
	global_store_short v253, v252, s[34:35]
	v_mul_f32_e32 v250, 0xbfb8aa3b, v12
	v_mul_f32_e32 v252, 0xbfb8aa3b, v13
	v_exp_f32_e32 v250, v250
	v_exp_f32_e32 v252, v252
	v_add_u32_e32 v251, 0x18c00, v124
	v_add_f32_e32 v250, 1.0, v250
	v_add_f32_e32 v252, 1.0, v252
	v_rcp_f32_e32 v250, v250
	v_rcp_f32_e32 v252, v252
	v_add_u32_e32 v253, 0x1a200, v124
	v_mul_f32_e32 v250, v12, v250
	v_mul_f32_e32 v252, v13, v252
	v_mul_f32_e32 v250, v28, v250
	v_mul_f32_e32 v252, v29, v252
	v_cvt_pk_bf16_f32 v250, v250, v250
	v_cvt_pk_bf16_f32 v252, v252, v252
	global_store_short v251, v250, s[34:35]
	global_store_short v253, v252, s[34:35]
	v_mul_f32_e32 v250, 0xbfb8aa3b, v14
	v_mul_f32_e32 v252, 0xbfb8aa3b, v15
	v_exp_f32_e32 v250, v250
	v_exp_f32_e32 v252, v252
	v_add_u32_e32 v251, 0x21000, v124
	v_add_f32_e32 v250, 1.0, v250
	v_add_f32_e32 v252, 1.0, v252
	v_rcp_f32_e32 v250, v250
	v_rcp_f32_e32 v252, v252
	v_add_u32_e32 v253, 0x22600, v124
	v_mul_f32_e32 v250, v14, v250
	v_mul_f32_e32 v252, v15, v252
	v_mul_f32_e32 v250, v30, v250
	v_mul_f32_e32 v252, v31, v252
	v_cvt_pk_bf16_f32 v250, v250, v250
	v_cvt_pk_bf16_f32 v252, v252, v252
	global_store_short v251, v250, s[34:35]
	global_store_short v253, v252, s[34:35]
	v_mul_f32_e32 v250, 0xbfb8aa3b, v16
	v_mul_f32_e32 v252, 0xbfb8aa3b, v17
	v_exp_f32_e32 v250, v250
	v_exp_f32_e32 v252, v252
	v_add_u32_e32 v251, 0x23c00, v124
	v_add_f32_e32 v250, 1.0, v250
	v_add_f32_e32 v252, 1.0, v252
	v_rcp_f32_e32 v250, v250
	v_rcp_f32_e32 v252, v252
	v_add_u32_e32 v253, 0x25200, v124
	v_mul_f32_e32 v250, v16, v250
	v_mul_f32_e32 v252, v17, v252
	v_mul_f32_e32 v250, v32, v250
	v_mul_f32_e32 v252, v33, v252
	v_cvt_pk_bf16_f32 v250, v250, v250
	v_cvt_pk_bf16_f32 v252, v252, v252
	global_store_short v251, v250, s[34:35]
	global_store_short v253, v252, s[34:35]
	v_mul_f32_e32 v250, 0xbfb8aa3b, v34
	v_mul_f32_e32 v252, 0xbfb8aa3b, v35
	v_exp_f32_e32 v250, v250
	v_exp_f32_e32 v252, v252
	v_add_u32_e32 v251, 0x2c000, v124
	v_add_f32_e32 v250, 1.0, v250
	v_add_f32_e32 v252, 1.0, v252
	v_rcp_f32_e32 v250, v250
	v_rcp_f32_e32 v252, v252
	v_add_u32_e32 v253, 0x2d600, v124
	v_mul_f32_e32 v250, v34, v250
	v_mul_f32_e32 v252, v35, v252
	v_mul_f32_e32 v250, v50, v250
	v_mul_f32_e32 v252, v51, v252
	v_cvt_pk_bf16_f32 v250, v250, v250
	v_cvt_pk_bf16_f32 v252, v252, v252
	global_store_short v251, v250, s[34:35]
	global_store_short v253, v252, s[34:35]
	v_mul_f32_e32 v250, 0xbfb8aa3b, v36
	v_mul_f32_e32 v252, 0xbfb8aa3b, v37
	v_exp_f32_e32 v250, v250
	v_exp_f32_e32 v252, v252
	v_add_u32_e32 v251, 0x2ec00, v124
	v_add_f32_e32 v250, 1.0, v250
	v_add_f32_e32 v252, 1.0, v252
	v_rcp_f32_e32 v250, v250
	v_rcp_f32_e32 v252, v252
	v_add_u32_e32 v253, 0x30200, v124
	v_mul_f32_e32 v250, v36, v250
	v_mul_f32_e32 v252, v37, v252
; #define GAS __attribute__((address_space(1)))
; DI int opaque0() { int z = 0; asm volatile("" : "+v"(z)); return z; }
; template <int AI>
; DI void gu_tile(char* wsb, int sub, int m0, int n0, char* lds) {
;     ...
;   const int m0e = m0 + opaque0();
;   const int hc = (n0 >> 1) + wb * 32 + r;
;   GAS u16* HIDu = uptr(HID);
;   const unsigned ib = (unsigned)((m0e + wa * 32 * AI + 4 * h) * 2816 + hc);
; #pragma unroll
;   for (int ai = 0; ai < AI; ++ai)
; #pragma unroll
;     for (int reg = 0; reg < 16; ++reg) {
;       float g = acc[ai][0][reg], u = acc[ai][1][reg];
;       float v = g * __builtin_amdgcn_rcpf(1.f + __expf(-g)) * u;
;       HIDu[ib + (unsigned)((ai * 32 + (reg & 3) + 8 * (reg >> 2)) * 2816)] = f2bf(v);
;       if ((reg & 7) == 7) __builtin_amdgcn_sched_barrier(0);
;     }
	v_mul_f32_e32 v250, v52, v250
	v_mul_f32_e32 v252, v53, v252
	v_cvt_pk_bf16_f32 v250, v250, v250
	v_cvt_pk_bf16_f32 v252, v252, v252
	global_store_short v251, v250, s[34:35]
	global_store_short v253, v252, s[34:35]
	v_mul_f32_e32 v250, 0xbfb8aa3b, v38
	v_mul_f32_e32 v252, 0xbfb8aa3b, v39
	v_exp_f32_e32 v250, v250
	v_exp_f32_e32 v252, v252
	v_add_u32_e32 v251, 0x37000, v124
	v_add_f32_e32 v250, 1.0, v250
	v_add_f32_e32 v252, 1.0, v252
	v_rcp_f32_e32 v250, v250
	v_rcp_f32_e32 v252, v252
	v_add_u32_e32 v253, 0x38600, v124
	v_mul_f32_e32 v250, v38, v250
	v_mul_f32_e32 v252, v39, v252
	v_mul_f32_e32 v250, v54, v250
	v_mul_f32_e32 v252, v55, v252
	v_cvt_pk_bf16_f32 v250, v250, v250
	v_cvt_pk_bf16_f32 v252, v252, v252
	global_store_short v251, v250, s[34:35]
	global_store_short v253, v252, s[34:35]
	v_mul_f32_e32 v250, 0xbfb8aa3b, v40
	v_mul_f32_e32 v252, 0xbfb8aa3b, v41
	v_exp_f32_e32 v250, v250
	v_exp_f32_e32 v252, v252
	v_add_u32_e32 v251, 0x39c00, v124
	v_add_f32_e32 v250, 1.0, v250
	v_add_f32_e32 v252, 1.0, v252
	v_rcp_f32_e32 v250, v250
	v_rcp_f32_e32 v252, v252
	v_add_u32_e32 v253, 0x3b200, v124
	v_mul_f32_e32 v250, v40, v250
	v_mul_f32_e32 v252, v41, v252
	v_mul_f32_e32 v250, v56, v250
	v_mul_f32_e32 v252, v57, v252
	v_cvt_pk_bf16_f32 v250, v250, v250
	v_cvt_pk_bf16_f32 v252, v252, v252
	global_store_short v251, v250, s[34:35]
	global_store_short v253, v252, s[34:35]
	v_mul_f32_e32 v250, 0xbfb8aa3b, v42
	v_mul_f32_e32 v252, 0xbfb8aa3b, v43
	v_exp_f32_e32 v250, v250
	v_exp_f32_e32 v252, v252
	v_add_u32_e32 v251, 0x42000, v124
	v_add_f32_e32 v250, 1.0, v250
	v_add_f32_e32 v252, 1.0, v252
	v_rcp_f32_e32 v250, v250
	v_rcp_f32_e32 v252, v252
	v_add_u32_e32 v253, 0x43600, v124
	v_mul_f32_e32 v250, v42, v250
	v_mul_f32_e32 v252, v43, v252
	v_mul_f32_e32 v250, v58, v250
	v_mul_f32_e32 v252, v59, v252
	v_cvt_pk_bf16_f32 v250, v250, v250
	v_cvt_pk_bf16_f32 v252, v252, v252
	global_store_short v251, v250, s[34:35]
	global_store_short v253, v252, s[34:35]
	v_mul_f32_e32 v250, 0xbfb8aa3b, v44
	v_mul_f32_e32 v252, 0xbfb8aa3b, v45
	v_exp_f32_e32 v250, v250
	v_exp_f32_e32 v252, v252
	v_add_u32_e32 v251, 0x44c00, v124
	v_add_f32_e32 v250, 1.0, v250
	v_add_f32_e32 v252, 1.0, v252
	v_rcp_f32_e32 v250, v250
	v_rcp_f32_e32 v252, v252
	v_add_u32_e32 v253, 0x46200, v124
	v_mul_f32_e32 v250, v44, v250
	v_mul_f32_e32 v252, v45, v252
	v_mul_f32_e32 v250, v60, v250
	v_mul_f32_e32 v252, v61, v252
	v_cvt_pk_bf16_f32 v250, v250, v250
	v_cvt_pk_bf16_f32 v252, v252, v252
	global_store_short v251, v250, s[34:35]
	global_store_short v253, v252, s[34:35]
	v_mul_f32_e32 v250, 0xbfb8aa3b, v46
	v_mul_f32_e32 v252, 0xbfb8aa3b, v47
	v_exp_f32_e32 v250, v250
	v_exp_f32_e32 v252, v252
	v_add_u32_e32 v251, 0x4d000, v124
	v_add_f32_e32 v250, 1.0, v250
	v_add_f32_e32 v252, 1.0, v252
	v_rcp_f32_e32 v250, v250
	v_rcp_f32_e32 v252, v252
	v_add_u32_e32 v253, 0x4e600, v124
	v_mul_f32_e32 v250, v46, v250
	v_mul_f32_e32 v252, v47, v252
	v_mul_f32_e32 v250, v62, v250
	v_mul_f32_e32 v252, v63, v252
	v_cvt_pk_bf16_f32 v250, v250, v250
	v_cvt_pk_bf16_f32 v252, v252, v252
	global_store_short v251, v250, s[34:35]
	global_store_short v253, v252, s[34:35]
	v_mul_f32_e32 v250, 0xbfb8aa3b, v48
	v_mul_f32_e32 v252, 0xbfb8aa3b, v49
	v_exp_f32_e32 v250, v250
	v_exp_f32_e32 v252, v252
	v_add_u32_e32 v251, 0x4fc00, v124
	v_add_f32_e32 v250, 1.0, v250
	v_add_f32_e32 v252, 1.0, v252
	v_rcp_f32_e32 v250, v250
	v_rcp_f32_e32 v252, v252
	v_add_u32_e32 v253, 0x51200, v124
	v_mul_f32_e32 v250, v48, v250
	v_mul_f32_e32 v252, v49, v252
	v_mul_f32_e32 v250, v64, v250
	v_mul_f32_e32 v252, v65, v252
	v_cvt_pk_bf16_f32 v250, v250, v250
	v_cvt_pk_bf16_f32 v252, v252, v252
	global_store_short v251, v250, s[34:35]
	global_store_short v253, v252, s[34:35]
	v_mul_f32_e32 v250, 0xbfb8aa3b, v66
	v_mul_f32_e32 v252, 0xbfb8aa3b, v67
	v_exp_f32_e32 v250, v250
	v_exp_f32_e32 v252, v252
	v_add_u32_e32 v251, 0xb0000, v124
	v_add_f32_e32 v250, 1.0, v250
	v_add_f32_e32 v252, 1.0, v252
	v_rcp_f32_e32 v250, v250
	v_rcp_f32_e32 v252, v252
	v_add_u32_e32 v253, 0xb1600, v124
	v_mul_f32_e32 v250, v66, v250
	v_mul_f32_e32 v252, v67, v252
	v_mul_f32_e32 v250, v82, v250
	v_mul_f32_e32 v252, v83, v252
	v_cvt_pk_bf16_f32 v250, v250, v250
	v_cvt_pk_bf16_f32 v252, v252, v252
	global_store_short v251, v250, s[34:35]
	global_store_short v253, v252, s[34:35]
	v_mul_f32_e32 v250, 0xbfb8aa3b, v68
	v_mul_f32_e32 v252, 0xbfb8aa3b, v69
	v_exp_f32_e32 v250, v250
	v_exp_f32_e32 v252, v252
	v_add_u32_e32 v251, 0xb2c00, v124
	v_add_f32_e32 v250, 1.0, v250
	v_add_f32_e32 v252, 1.0, v252
	v_rcp_f32_e32 v250, v250
	v_rcp_f32_e32 v252, v252
	v_add_u32_e32 v253, 0xb4200, v124
	v_mul_f32_e32 v250, v68, v250
	v_mul_f32_e32 v252, v69, v252
	v_mul_f32_e32 v250, v84, v250
	v_mul_f32_e32 v252, v85, v252
	v_cvt_pk_bf16_f32 v250, v250, v250
	v_cvt_pk_bf16_f32 v252, v252, v252
	global_store_short v251, v250, s[34:35]
	global_store_short v253, v252, s[34:35]
	v_mul_f32_e32 v250, 0xbfb8aa3b, v70
	v_mul_f32_e32 v252, 0xbfb8aa3b, v71
	v_exp_f32_e32 v250, v250
	v_exp_f32_e32 v252, v252
	v_add_u32_e32 v251, 0xbb000, v124
	v_add_f32_e32 v250, 1.0, v250
	v_add_f32_e32 v252, 1.0, v252
	v_rcp_f32_e32 v250, v250
	v_rcp_f32_e32 v252, v252
	v_add_u32_e32 v253, 0xbc600, v124
	v_mul_f32_e32 v250, v70, v250
	v_mul_f32_e32 v252, v71, v252
	v_mul_f32_e32 v250, v86, v250
	v_mul_f32_e32 v252, v87, v252
	v_cvt_pk_bf16_f32 v250, v250, v250
	v_cvt_pk_bf16_f32 v252, v252, v252
	global_store_short v251, v250, s[34:35]
	global_store_short v253, v252, s[34:35]
	v_mul_f32_e32 v250, 0xbfb8aa3b, v72
	v_mul_f32_e32 v252, 0xbfb8aa3b, v73
	v_exp_f32_e32 v250, v250
	v_exp_f32_e32 v252, v252
; template <int AI>
; DI void gu_tile(char* wsb, int sub, int m0, int n0, char* lds) {
;     ...
;   const unsigned ib = (unsigned)((m0e + wa * 32 * AI + 4 * h) * 2816 + hc);
; #pragma unroll
;   for (int ai = 0; ai < AI; ++ai)
; #pragma unroll
;     for (int reg = 0; reg < 16; ++reg) {
;       float g = acc[ai][0][reg], u = acc[ai][1][reg];
;       float v = g * __builtin_amdgcn_rcpf(1.f + __expf(-g)) * u;
;       HIDu[ib + (unsigned)((ai * 32 + (reg & 3) + 8 * (reg >> 2)) * 2816)] = f2bf(v);
;       if ((reg & 7) == 7) __builtin_amdgcn_sched_barrier(0);
;     }
	v_add_u32_e32 v251, 0xbdc00, v124
	v_add_f32_e32 v250, 1.0, v250
	v_add_f32_e32 v252, 1.0, v252
	v_rcp_f32_e32 v250, v250
	v_rcp_f32_e32 v252, v252
	v_add_u32_e32 v253, 0xbf200, v124
	v_mul_f32_e32 v250, v72, v250
	v_mul_f32_e32 v252, v73, v252
	v_mul_f32_e32 v250, v88, v250
	v_mul_f32_e32 v252, v89, v252
	v_cvt_pk_bf16_f32 v250, v250, v250
	v_cvt_pk_bf16_f32 v252, v252, v252
	global_store_short v251, v250, s[34:35]
	global_store_short v253, v252, s[34:35]
	v_mul_f32_e32 v250, 0xbfb8aa3b, v74
	v_mul_f32_e32 v252, 0xbfb8aa3b, v75
	v_exp_f32_e32 v250, v250
	v_exp_f32_e32 v252, v252
	v_add_u32_e32 v251, 0xc6000, v124
	v_add_f32_e32 v250, 1.0, v250
	v_add_f32_e32 v252, 1.0, v252
	v_rcp_f32_e32 v250, v250
	v_rcp_f32_e32 v252, v252
	v_add_u32_e32 v253, 0xc7600, v124
	v_mul_f32_e32 v250, v74, v250
	v_mul_f32_e32 v252, v75, v252
	v_mul_f32_e32 v250, v90, v250
	v_mul_f32_e32 v252, v91, v252
	v_cvt_pk_bf16_f32 v250, v250, v250
	v_cvt_pk_bf16_f32 v252, v252, v252
	global_store_short v251, v250, s[34:35]
	global_store_short v253, v252, s[34:35]
	v_mul_f32_e32 v250, 0xbfb8aa3b, v76
	v_mul_f32_e32 v252, 0xbfb8aa3b, v77
	v_exp_f32_e32 v250, v250
	v_exp_f32_e32 v252, v252
	v_add_u32_e32 v251, 0xc8c00, v124
	v_add_f32_e32 v250, 1.0, v250
	v_add_f32_e32 v252, 1.0, v252
	v_rcp_f32_e32 v250, v250
	v_rcp_f32_e32 v252, v252
	v_add_u32_e32 v253, 0xca200, v124
	v_mul_f32_e32 v250, v76, v250
	v_mul_f32_e32 v252, v77, v252
	v_mul_f32_e32 v250, v92, v250
	v_mul_f32_e32 v252, v93, v252
	v_cvt_pk_bf16_f32 v250, v250, v250
	v_cvt_pk_bf16_f32 v252, v252, v252
	global_store_short v251, v250, s[34:35]
	global_store_short v253, v252, s[34:35]
	v_mul_f32_e32 v250, 0xbfb8aa3b, v78
	v_mul_f32_e32 v252, 0xbfb8aa3b, v79
	v_exp_f32_e32 v250, v250
	v_exp_f32_e32 v252, v252
	v_add_u32_e32 v251, 0xd1000, v124
	v_add_f32_e32 v250, 1.0, v250
	v_add_f32_e32 v252, 1.0, v252
	v_rcp_f32_e32 v250, v250
	v_rcp_f32_e32 v252, v252
	v_add_u32_e32 v253, 0xd2600, v124
	v_mul_f32_e32 v250, v78, v250
	v_mul_f32_e32 v252, v79, v252
	v_mul_f32_e32 v250, v94, v250
	v_mul_f32_e32 v252, v95, v252
	v_cvt_pk_bf16_f32 v250, v250, v250
	v_cvt_pk_bf16_f32 v252, v252, v252
	global_store_short v251, v250, s[34:35]
	global_store_short v253, v252, s[34:35]
	v_mul_f32_e32 v250, 0xbfb8aa3b, v80
	v_mul_f32_e32 v252, 0xbfb8aa3b, v81
	v_exp_f32_e32 v250, v250
	v_exp_f32_e32 v252, v252
	v_add_u32_e32 v251, 0xd3c00, v124
	v_add_f32_e32 v250, 1.0, v250
	v_add_f32_e32 v252, 1.0, v252
	v_rcp_f32_e32 v250, v250
	v_rcp_f32_e32 v252, v252
	v_add_u32_e32 v253, 0xd5200, v124
	v_mul_f32_e32 v250, v80, v250
	v_mul_f32_e32 v252, v81, v252
	v_mul_f32_e32 v250, v96, v250
	v_mul_f32_e32 v252, v97, v252
	v_cvt_pk_bf16_f32 v250, v250, v250
	v_cvt_pk_bf16_f32 v252, v252, v252
	global_store_short v251, v250, s[34:35]
	global_store_short v253, v252, s[34:35]
	v_mul_f32_e32 v250, 0xbfb8aa3b, v98
	v_mul_f32_e32 v252, 0xbfb8aa3b, v99
	v_exp_f32_e32 v250, v250
	v_exp_f32_e32 v252, v252
	v_add_u32_e32 v251, 0xdc000, v124
	v_add_f32_e32 v250, 1.0, v250
	v_add_f32_e32 v252, 1.0, v252
	v_rcp_f32_e32 v250, v250
	v_rcp_f32_e32 v252, v252
	v_add_u32_e32 v253, 0xdd600, v124
	v_mul_f32_e32 v250, v98, v250
	v_mul_f32_e32 v252, v99, v252
	v_mul_f32_e32 v250, v214, v250
	v_mul_f32_e32 v252, v215, v252
	v_cvt_pk_bf16_f32 v250, v250, v250
	v_cvt_pk_bf16_f32 v252, v252, v252
	global_store_short v251, v250, s[34:35]
	global_store_short v253, v252, s[34:35]
	v_mul_f32_e32 v250, 0xbfb8aa3b, v100
	v_mul_f32_e32 v252, 0xbfb8aa3b, v101
	v_exp_f32_e32 v250, v250
	v_exp_f32_e32 v252, v252
	v_add_u32_e32 v251, 0xdec00, v124
	v_add_f32_e32 v250, 1.0, v250
	v_add_f32_e32 v252, 1.0, v252
	v_rcp_f32_e32 v250, v250
	v_rcp_f32_e32 v252, v252
	v_add_u32_e32 v253, 0xe0200, v124
	v_mul_f32_e32 v250, v100, v250
	v_mul_f32_e32 v252, v101, v252
	v_mul_f32_e32 v250, v216, v250
	v_mul_f32_e32 v252, v217, v252
	v_cvt_pk_bf16_f32 v250, v250, v250
	v_cvt_pk_bf16_f32 v252, v252, v252
	global_store_short v251, v250, s[34:35]
	global_store_short v253, v252, s[34:35]
	v_mul_f32_e32 v250, 0xbfb8aa3b, v102
	v_mul_f32_e32 v252, 0xbfb8aa3b, v103
	v_exp_f32_e32 v250, v250
	v_exp_f32_e32 v252, v252
; template <int AI>
; DI void gu_tile(char* wsb, int sub, int m0, int n0, char* lds) {
;     ...
;   const unsigned ib = (unsigned)((m0e + wa * 32 * AI + 4 * h) * 2816 + hc);
; #pragma unroll
;   for (int ai = 0; ai < AI; ++ai)
; #pragma unroll
;     for (int reg = 0; reg < 16; ++reg) {
;       float g = acc[ai][0][reg], u = acc[ai][1][reg];
;       float v = g * __builtin_amdgcn_rcpf(1.f + __expf(-g)) * u;
;       HIDu[ib + (unsigned)((ai * 32 + (reg & 3) + 8 * (reg >> 2)) * 2816)] = f2bf(v);
;       if ((reg & 7) == 7) __builtin_amdgcn_sched_barrier(0);
;     }
; }
; DI void phase_gu(const Params& p, char* wsb, int sub, int mrows, char* lds) {
;   int mt, nt;
;   for (int rnd = 0; next_tile(rnd, 128, 44, mt, nt); ++rnd) gu_tile<2>(wsb, sub, mt * 128, nt * 128, lds);
	v_add_u32_e32 v251, 0xe7000, v124
	v_add_f32_e32 v250, 1.0, v250
	v_add_f32_e32 v252, 1.0, v252
	v_rcp_f32_e32 v250, v250
	v_rcp_f32_e32 v252, v252
	v_add_u32_e32 v253, 0xe8600, v124
	v_mul_f32_e32 v250, v102, v250
	v_mul_f32_e32 v252, v103, v252
	v_mul_f32_e32 v250, v218, v250
	v_mul_f32_e32 v252, v219, v252
	v_cvt_pk_bf16_f32 v250, v250, v250
	v_cvt_pk_bf16_f32 v252, v252, v252
	global_store_short v251, v250, s[34:35]
	global_store_short v253, v252, s[34:35]
	v_mul_f32_e32 v250, 0xbfb8aa3b, v104
	v_mul_f32_e32 v252, 0xbfb8aa3b, v105
	v_exp_f32_e32 v250, v250
	v_exp_f32_e32 v252, v252
	v_add_u32_e32 v251, 0xe9c00, v124
	v_add_f32_e32 v250, 1.0, v250
	v_add_f32_e32 v252, 1.0, v252
	v_rcp_f32_e32 v250, v250
	v_rcp_f32_e32 v252, v252
	v_add_u32_e32 v253, 0xeb200, v124
	v_mul_f32_e32 v250, v104, v250
	v_mul_f32_e32 v252, v105, v252
	v_mul_f32_e32 v250, v220, v250
	v_mul_f32_e32 v252, v221, v252
	v_cvt_pk_bf16_f32 v250, v250, v250
	v_cvt_pk_bf16_f32 v252, v252, v252
	global_store_short v251, v250, s[34:35]
	global_store_short v253, v252, s[34:35]
	v_mul_f32_e32 v250, 0xbfb8aa3b, v106
	v_mul_f32_e32 v252, 0xbfb8aa3b, v107
	v_exp_f32_e32 v250, v250
	v_exp_f32_e32 v252, v252
	v_add_u32_e32 v251, 0xf2000, v124
	v_add_f32_e32 v250, 1.0, v250
	v_add_f32_e32 v252, 1.0, v252
	v_rcp_f32_e32 v250, v250
	v_rcp_f32_e32 v252, v252
	v_add_u32_e32 v253, 0xf3600, v124
	v_mul_f32_e32 v250, v106, v250
	v_mul_f32_e32 v252, v107, v252
	v_mul_f32_e32 v250, v222, v250
	v_mul_f32_e32 v252, v223, v252
	v_cvt_pk_bf16_f32 v250, v250, v250
	v_cvt_pk_bf16_f32 v252, v252, v252
	global_store_short v251, v250, s[34:35]
	global_store_short v253, v252, s[34:35]
	v_mul_f32_e32 v250, 0xbfb8aa3b, v108
	v_mul_f32_e32 v252, 0xbfb8aa3b, v109
	v_exp_f32_e32 v250, v250
	v_exp_f32_e32 v252, v252
	v_add_u32_e32 v251, 0xf4c00, v124
	v_add_f32_e32 v250, 1.0, v250
	v_add_f32_e32 v252, 1.0, v252
	v_rcp_f32_e32 v250, v250
	v_rcp_f32_e32 v252, v252
	v_add_u32_e32 v253, 0xf6200, v124
	v_mul_f32_e32 v250, v108, v250
	v_mul_f32_e32 v252, v109, v252
	v_mul_f32_e32 v250, v224, v250
	v_mul_f32_e32 v252, v225, v252
	v_cvt_pk_bf16_f32 v250, v250, v250
	v_cvt_pk_bf16_f32 v252, v252, v252
	global_store_short v251, v250, s[34:35]
	global_store_short v253, v252, s[34:35]
	v_mul_f32_e32 v250, 0xbfb8aa3b, v110
	v_mul_f32_e32 v252, 0xbfb8aa3b, v111
	v_exp_f32_e32 v250, v250
	v_exp_f32_e32 v252, v252
	v_add_u32_e32 v251, 0xfd000, v124
	v_add_f32_e32 v250, 1.0, v250
	v_add_f32_e32 v252, 1.0, v252
	v_rcp_f32_e32 v250, v250
	v_rcp_f32_e32 v252, v252
	v_add_u32_e32 v253, 0xfe600, v124
	v_mul_f32_e32 v250, v110, v250
	v_mul_f32_e32 v252, v111, v252
	v_mul_f32_e32 v250, v226, v250
	v_mul_f32_e32 v252, v227, v252
	v_cvt_pk_bf16_f32 v250, v250, v250
	v_cvt_pk_bf16_f32 v252, v252, v252
	global_store_short v251, v250, s[34:35]
	global_store_short v253, v252, s[34:35]
	v_mul_f32_e32 v250, 0xbfb8aa3b, v112
	v_mul_f32_e32 v252, 0xbfb8aa3b, v113
	v_exp_f32_e32 v250, v250
	v_exp_f32_e32 v252, v252
	v_add_u32_e32 v251, 0xffc00, v124
	v_add_f32_e32 v250, 1.0, v250
	v_add_f32_e32 v252, 1.0, v252
	v_rcp_f32_e32 v250, v250
	v_rcp_f32_e32 v252, v252
	v_add_u32_e32 v253, 0x101200, v124
	v_mul_f32_e32 v250, v112, v250
	v_mul_f32_e32 v252, v113, v252
	v_mul_f32_e32 v250, v228, v250
	v_mul_f32_e32 v252, v229, v252
	v_cvt_pk_bf16_f32 v250, v250, v250
	v_cvt_pk_bf16_f32 v252, v252, v252
	global_store_short v251, v250, s[34:35]
	global_store_short v253, v252, s[34:35]
	s_cmp_lt_u32 s32, 5
	s_cbranch_scc0 .Lgu1_rdone
	s_lshr_b32 s37, s40, 3
	s_lshl_b32 s50, s32, 3
	s_add_u32 s37, s37, s50
	s_and_b32 s50, s40, 7
	s_lshl_b32 s51, s41, 3
	s_add_u32 s50, s50, s51
	s_mul_i32 s51, s50, 0x160000
	s_lshl_b32 s52, s37, 7
	s_add_u32 s51, s51, s52
	s_add_u32 s34, s6, s51
	s_addc_u32 s35, s7, 0
	s_branch .Lgu1_round
.Lgu1_rdone:
	s_lshr_b32 s37, s40, 4
	s_add_u32 s37, s37, 40
	s_and_b32 s50, s40, 15
	s_lshl_b32 s51, s41, 4
	s_add_u32 s50, s50, s51
	s_lshr_b32 s51, s50, 3
	s_mul_i32 s51, s51, 0x160
	s_lshl_b32 s52, s37, 3
	s_add_u32 s51, s51, s52
	s_and_b32 s52, s50, 7
	s_add_u32 s14, s51, s52
	s_lshl_b32 s15, s14, 7
	s_mov_b32 s52, 1
	v_writelane_b32 v245, s52, 0

; #define MFMA(a, b, c) __builtin_amdgcn_mfma_f32_32x32x16_bf16((a), (b), (c), 0, 0, 0)
; #define TIDX opaque_tid()
; DI void gemm_stage_w(const u16* __restrict__ A, int lda, const u16* __restrict__ B, int ldb, char* buf, int tid) {
; #pragma unroll
;   for (int i = 0; i < 2; ++i) {
;     const int S = tid + NTHR * i, row = S >> 2, c = (S & 3) ^ ((row >> 2) & 3);
;     __builtin_amdgcn_global_load_lds((const unsigned*)(A + (size_t)row * lda + c * 8), (__attribute__((address_space(3))) unsigned*)(buf + S * 16), 16, 0, 0);
;   }
; #pragma unroll
;   for (int i = 0; i < 4; ++i) {
;     const int S = tid + NTHR * i, row = S >> 2, c = (S & 3) ^ ((row >> 2) & 3);
;     __builtin_amdgcn_global_load_lds((const unsigned*)(B + (size_t)row * ldb + c * 8), (__attribute__((address_space(3))) unsigned*)(buf + 8192 + S * 16), 16, 0, 0);
;   }
; }
; DI void gemm_tile_w(const u16* __restrict__ A, int lda, const u16* __restrict__ B, int ldb, int nk, bool swap,
;                     f32x16 (&acc)[2][4], char* lds) {
;   const int tid = TIDX, lane = tid & 63, wid = tid >> 6;
;   gemm_stage_w(A, lda, B, ldb, lds, tid);
;   asm volatile("s_waitcnt vmcnt(0)" ::: "memory");
;   __syncthreads();
;   const int r = lane & 31, h = lane >> 5, sw = (r >> 2) & 3;
;   const int wa = swap ? wid : (wid >> 1), wb = swap ? 0 : (wid & 1);
;   const int offF = (swap ? 8192 : 0) + (wa * 64 + r) * 64;
;   const int offS = (swap ? 0 : 8192) + (wb * 128 + r) * 64;
;   for (int kt = 0; kt < nk; ++kt) {
;     const char* cur = lds + (kt & 1) * 24576;
;     if (kt + 1 < nk) gemm_stage_w(A + (kt + 1) * 32, lda, B + (kt + 1) * 32, ldb, lds + ((kt + 1) & 1) * 24576, tid);
; #pragma unroll
;     for (int ks = 0; ks < 2; ++ks) {
;       const int co = ((ks * 2 + h) ^ sw) << 4;
;       s16x8 f0 = *(const s16x8*)(cur + offF + co), f1 = *(const s16x8*)(cur + offF + 2048 + co);
; #pragma unroll
;       for (int si = 0; si < 4; ++si) {
;         s16x8 sb = *(const s16x8*)(cur + offS + si * 2048 + co);
;         acc[0][si] = MFMA(f0, sb, acc[0][si]);
;         acc[1][si] = MFMA(f1, sb, acc[1][si]);
;       }
;     }
;     asm volatile("s_waitcnt vmcnt(0)" ::: "memory");
;     __syncthreads();
;   }
; }
.LBB0_1204:
	s_or_b64 exec, exec, s[6:7]
	s_mov_b32 s6, s19
	s_mov_b64 s[8:9], s[20:21]
	s_waitcnt lgkmcnt(0)
	s_barrier
	s_mov_b64 s[14:15], s[26:27]
	s_add_u32 s8, s14, s6
	v_readlane_b32 s6, v242, 3
	v_readlane_b32 s7, v242, 4
	s_addc_u32 s9, s15, 0
	s_and_b64 vcc, exec, s[6:7]
	s_mov_b64 s[10:11], s[22:23]
	s_mov_b64 s[12:13], s[24:25]
	s_cbranch_vccnz .LBB0_1208
	s_add_u32 s10, s8, 0x77b7000
	s_addc_u32 s11, s9, 0
	s_add_u32 s12, s8, 0x1d537000
	s_addc_u32 s13, s9, 0
	s_add_u32 s6, s8, 0x9bb7000
	s_addc_u32 s7, s9, 0
	v_readlane_b32 s14, v243, 18
	v_readlane_b32 s15, v243, 5
	v_readlane_b32 s53, v243, 6
	v_readlane_b32 s56, v243, 7
	s_mov_b32 s57, 0x1ffffc0
	s_movk_i32 s64, 0xb00
	s_mov_b64 s[66:67], 0x200
	s_mov_b64 s[68:69], 0x80
	s_mov_b64 s[70:71], 0x180
	s_mov_b64 s[72:73], 0x280
	s_mov_b64 s[74:75], 0x300
	s_mov_b64 s[76:77], 0x380
	s_mov_b64 s[80:81], 0x400
	s_mov_b64 s[82:83], 0x480
	s_mov_b64 s[84:85], 0x500
	s_mov_b64 s[88:89], 0x580
	s_mov_b64 vcc, 0x600
	s_waitcnt vmcnt(0)
	s_cmpk_lg_u32 s92, 0x200
	s_cbranch_scc1 .LBB0_1206
	v_and_b32_e32 v0, 31, v178
	v_bfe_u32 v122, v178, 5, 1
	v_bfe_u32 v123, v178, 2, 2
	v_xor_b32_e32 v122, v122, v123
	v_lshlrev_b32_e32 v122, 4, v122
	v_bfe_u32 v123, v178, 7, 1
	v_lshl_add_u32 v123, v123, 6, v0
	v_lshl_add_u32 v142, v123, 6, v122
	v_xor_b32_e32 v143, 32, v142
	v_bfe_u32 v123, v178, 6, 1
	v_lshl_add_u32 v123, v123, 6, v0
	v_lshl_add_u32 v144, v123, 6, v122
	v_add_u32_e32 v144, 0xc000, v144
	v_xor_b32_e32 v145, 32, v144
	v_bfe_u32 v122, v178, 7, 1
	v_lshlrev_b32_e32 v122, 6, v122
	v_bfe_u32 v123, v178, 5, 1
	v_lshl_add_u32 v122, v123, 2, v122
	v_mul_u32_u24_e32 v122, 0xb00, v122
	v_bfe_u32 v123, v178, 6, 1
	v_lshl_add_u32 v123, v123, 5, v0
	v_add_u32_e32 v122, v122, v123
	v_lshlrev_b32_e32 v124, 1, v122
	v_lshrrev_b32_e32 v0, 2, v178
	v_bfe_u32 v122, v178, 4, 2
	v_and_b32_e32 v123, 3, v178
	v_xor_b32_e32 v122, v122, v123
	v_lshlrev_b32_e32 v122, 4, v122
	v_lshl_add_u32 v126, v0, 11, v122
	v_add_u32_e32 v127, 0x20000, v126
	v_add_u32_e32 v128, 0x40000, v126
	v_add_u32_e32 v129, 0x60000, v126
	v_lshrrev_b32_e32 v0, 6, v178
	s_nop 1
	v_readfirstlane_b32 s18, v0
	s_lshl_b32 s18, s18, 10
	s_and_b32 s41, s96, 7
	s_lshr_b32 s40, s96, 3
	s_mov_b32 s32, 0
	s_lshr_b32 s37, s40, 3
	s_lshl_b32 s50, s32, 3
	s_add_u32 s37, s37, s50
	s_and_b32 s50, s40, 7
	s_lshl_b32 s51, s41, 3
	s_add_u32 s50, s50, s51
	s_lshl_b32 s51, s50, 19
	s_add_u32 s16, s10, s51
	s_addc_u32 s17, s11, 0
	s_lshl_b32 s51, s37, 18
	s_add_u32 s28, s12, s51
	s_addc_u32 s29, s13, 0
	s_lshr_b32 s37, s40, 3
	s_lshl_b32 s50, s32, 3
	s_add_u32 s37, s37, s50
	s_and_b32 s50, s40, 7
	s_lshl_b32 s51, s41, 3
	s_add_u32 s50, s50, s51
	s_mul_i32 s51, s50, 0x160000
	s_lshl_b32 s52, s37, 7
	s_add_u32 s51, s51, s52
	s_add_u32 s34, s6, s51
	s_addc_u32 s35, s7, 0
	s_add_u32 m0, s18, 0
	s_nop 0
	global_load_lds_dwordx4 v126, s[16:17]
	s_add_u32 m0, s18, 4096
	s_nop 0
	global_load_lds_dwordx4 v127, s[16:17]
	s_add_u32 m0, s18, 8192
	s_nop 0
	global_load_lds_dwordx4 v128, s[16:17]
	s_add_u32 m0, s18, 12288
	s_nop 0
	global_load_lds_dwordx4 v129, s[16:17]
	s_add_u32 m0, s18, 49152
	s_nop 0
	global_load_lds_dwordx4 v126, s[28:29]
	s_add_u32 m0, s18, 53248
	s_nop 0
	global_load_lds_dwordx4 v127, s[28:29]
	s_add_u32 s16, s16, 64
	s_addc_u32 s17, s17, 0
	s_add_u32 s28, s28, 64
	s_addc_u32 s29, s29, 0
	s_add_u32 m0, s18, 16384
	s_nop 0
	global_load_lds_dwordx4 v126, s[16:17]
	s_add_u32 m0, s18, 20480
	s_nop 0
	global_load_lds_dwordx4 v127, s[16:17]
	s_add_u32 m0, s18, 24576
	s_nop 0
	global_load_lds_dwordx4 v128, s[16:17]
	s_add_u32 m0, s18, 28672
	s_nop 0
	global_load_lds_dwordx4 v129, s[16:17]
	s_add_u32 m0, s18, 57344
	s_nop 0
	global_load_lds_dwordx4 v126, s[28:29]
	s_add_u32 m0, s18, 61440
	s_nop 0
	global_load_lds_dwordx4 v127, s[28:29]
	s_add_u32 s16, s16, 64
	s_addc_u32 s17, s17, 0
	s_add_u32 s28, s28, 64
	s_addc_u32 s29, s29, 0
	s_waitcnt vmcnt(6)
	s_barrier
	ds_read_b128 v[114:117], v142 offset:0
	ds_read_b128 v[230:233], v144 offset:0
	ds_read_b128 v[234:237], v144 offset:2048
	ds_read_b128 v[118:121], v142 offset:2048
	ds_read_b128 v[134:137], v142 offset:8192
	ds_read_b128 v[138:141], v142 offset:10240
	ds_read_b128 v[238:241], v145 offset:0
	ds_read_b128 v[246:249], v145 offset:2048
	s_add_u32 m0, s18, 32768
	s_nop 0
	global_load_lds_dwordx4 v126, s[16:17]
	s_add_u32 m0, s18, 36864
	s_nop 0
	global_load_lds_dwordx4 v127, s[16:17]
	s_add_u32 m0, s18, 40960
	s_nop 0
	global_load_lds_dwordx4 v128, s[16:17]
	s_add_u32 m0, s18, 45056
	s_nop 0
	global_load_lds_dwordx4 v129, s[16:17]
	s_add_u32 m0, s18, 65664
	s_nop 0
	global_load_lds_dwordx4 v126, s[28:29]
	s_add_u32 m0, s18, 69760
	s_nop 0
	global_load_lds_dwordx4 v127, s[28:29]
	s_add_u32 s16, s16, 64
	s_addc_u32 s17, s17, 0
	s_add_u32 s28, s28, 64
	s_addc_u32 s29, s29, 0
	s_waitcnt lgkmcnt(6)
	v_mfma_f32_32x32x16_bf16 v[2:17], v[114:117], v[230:233], 0
	s_waitcnt lgkmcnt(5)
	v_mfma_f32_32x32x16_bf16 v[18:33], v[114:117], v[234:237], 0
	ds_read_b128 v[114:117], v143 offset:0
	s_waitcnt lgkmcnt(5)
	v_mfma_f32_32x32x16_bf16 v[34:49], v[118:121], v[230:233], 0
	v_mfma_f32_32x32x16_bf16 v[50:65], v[118:121], v[234:237], 0
	ds_read_b128 v[118:121], v143 offset:2048
	s_waitcnt lgkmcnt(5)
	v_mfma_f32_32x32x16_bf16 v[66:81], v[134:137], v[230:233], 0
	v_mfma_f32_32x32x16_bf16 v[82:97], v[134:137], v[234:237], 0
	ds_read_b128 v[134:137], v143 offset:8192
	s_waitcnt lgkmcnt(5)
	v_mfma_f32_32x32x16_bf16 v[98:113], v[138:141], v[230:233], 0
	v_mfma_f32_32x32x16_bf16 v[214:229], v[138:141], v[234:237], 0
	ds_read_b128 v[138:141], v143 offset:10240
	s_waitcnt lgkmcnt(3)
	v_mfma_f32_32x32x16_bf16 v[2:17], v[114:117], v[238:241], v[2:17]
	v_mfma_f32_32x32x16_bf16 v[18:33], v[114:117], v[246:249], v[18:33]
	s_waitcnt lgkmcnt(2)
	v_mfma_f32_32x32x16_bf16 v[34:49], v[118:121], v[238:241], v[34:49]
	v_mfma_f32_32x32x16_bf16 v[50:65], v[118:121], v[246:249], v[50:65]
	s_waitcnt lgkmcnt(1)
	v_mfma_f32_32x32x16_bf16 v[66:81], v[134:137], v[238:241], v[66:81]
	v_mfma_f32_32x32x16_bf16 v[82:97], v[134:137], v[246:249], v[82:97]
	s_waitcnt lgkmcnt(0)
	v_mfma_f32_32x32x16_bf16 v[98:113], v[138:141], v[238:241], v[98:113]
	v_mfma_f32_32x32x16_bf16 v[214:229], v[138:141], v[246:249], v[214:229]
	s_waitcnt vmcnt(6)
	s_barrier
; #define MFMA(a, b, c) __builtin_amdgcn_mfma_f32_32x32x16_bf16((a), (b), (c), 0, 0, 0)
; #define TIDX opaque_tid()
; DI void gemm_stage_w(const u16* __restrict__ A, int lda, const u16* __restrict__ B, int ldb, char* buf, int tid) {
; #pragma unroll
;   for (int i = 0; i < 2; ++i) {
;     const int S = tid + NTHR * i, row = S >> 2, c = (S & 3) ^ ((row >> 2) & 3);
;     __builtin_amdgcn_global_load_lds((const unsigned*)(A + (size_t)row * lda + c * 8), (__attribute__((address_space(3))) unsigned*)(buf + S * 16), 16, 0, 0);
;   }
; #pragma unroll
;   for (int i = 0; i < 4; ++i) {
;     const int S = tid + NTHR * i, row = S >> 2, c = (S & 3) ^ ((row >> 2) & 3);
;     __builtin_amdgcn_global_load_lds((const unsigned*)(B + (size_t)row * ldb + c * 8), (__attribute__((address_space(3))) unsigned*)(buf + 8192 + S * 16), 16, 0, 0);
;   }
; }
; DI void gemm_tile_w(const u16* __restrict__ A, int lda, const u16* __restrict__ B, int ldb, int nk, bool swap,
;                     f32x16 (&acc)[2][4], char* lds) {
;   const int tid = TIDX, lane = tid & 63, wid = tid >> 6;
;   gemm_stage_w(A, lda, B, ldb, lds, tid);
;   asm volatile("s_waitcnt vmcnt(0)" ::: "memory");
;   __syncthreads();
;   const int r = lane & 31, h = lane >> 5, sw = (r >> 2) & 3;
;   const int wa = swap ? wid : (wid >> 1), wb = swap ? 0 : (wid & 1);
;   const int offF = (swap ? 8192 : 0) + (wa * 64 + r) * 64;
;   const int offS = (swap ? 0 : 8192) + (wb * 128 + r) * 64;
;   for (int kt = 0; kt < nk; ++kt) {
;     const char* cur = lds + (kt & 1) * 24576;
;     if (kt + 1 < nk) gemm_stage_w(A + (kt + 1) * 32, lda, B + (kt + 1) * 32, ldb, lds + ((kt + 1) & 1) * 24576, tid);
; #pragma unroll
;     for (int ks = 0; ks < 2; ++ks) {
;       const int co = ((ks * 2 + h) ^ sw) << 4;
;       s16x8 f0 = *(const s16x8*)(cur + offF + co), f1 = *(const s16x8*)(cur + offF + 2048 + co);
; #pragma unroll
;       for (int si = 0; si < 4; ++si) {
;         s16x8 sb = *(const s16x8*)(cur + offS + si * 2048 + co);
;         acc[0][si] = MFMA(f0, sb, acc[0][si]);
;         acc[1][si] = MFMA(f1, sb, acc[1][si]);
;       }
;     }
;     asm volatile("s_waitcnt vmcnt(0)" ::: "memory");
;     __syncthreads();
;   }
; }
	ds_read_b128 v[114:117], v142 offset:16384
	ds_read_b128 v[230:233], v144 offset:8192
	ds_read_b128 v[234:237], v144 offset:10240
	ds_read_b128 v[118:121], v142 offset:18432
	ds_read_b128 v[134:137], v142 offset:24576
	ds_read_b128 v[138:141], v142 offset:26624
	ds_read_b128 v[238:241], v145 offset:8192
	ds_read_b128 v[246:249], v145 offset:10240
	s_add_u32 m0, s18, 0
	s_nop 0
	global_load_lds_dwordx4 v126, s[16:17]
	s_add_u32 m0, s18, 4096
	s_nop 0
	global_load_lds_dwordx4 v127, s[16:17]
	s_add_u32 m0, s18, 8192
	s_nop 0
	global_load_lds_dwordx4 v128, s[16:17]
	s_add_u32 m0, s18, 12288
	s_nop 0
	global_load_lds_dwordx4 v129, s[16:17]
	s_add_u32 m0, s18, 49152
	s_nop 0
	global_load_lds_dwordx4 v126, s[28:29]
	s_add_u32 m0, s18, 53248
	s_nop 0
	global_load_lds_dwordx4 v127, s[28:29]
	s_add_u32 s16, s16, 64
	s_addc_u32 s17, s17, 0
	s_add_u32 s28, s28, 64
	s_addc_u32 s29, s29, 0
	s_waitcnt lgkmcnt(6)
	v_mfma_f32_32x32x16_bf16 v[2:17], v[114:117], v[230:233], v[2:17]
	s_waitcnt lgkmcnt(5)
	v_mfma_f32_32x32x16_bf16 v[18:33], v[114:117], v[234:237], v[18:33]
	ds_read_b128 v[114:117], v143 offset:16384
	s_waitcnt lgkmcnt(5)
	v_mfma_f32_32x32x16_bf16 v[34:49], v[118:121], v[230:233], v[34:49]
	v_mfma_f32_32x32x16_bf16 v[50:65], v[118:121], v[234:237], v[50:65]
	ds_read_b128 v[118:121], v143 offset:18432
	s_waitcnt lgkmcnt(5)
	v_mfma_f32_32x32x16_bf16 v[66:81], v[134:137], v[230:233], v[66:81]
	v_mfma_f32_32x32x16_bf16 v[82:97], v[134:137], v[234:237], v[82:97]
	ds_read_b128 v[134:137], v143 offset:24576
	s_waitcnt lgkmcnt(5)
	v_mfma_f32_32x32x16_bf16 v[98:113], v[138:141], v[230:233], v[98:113]
	v_mfma_f32_32x32x16_bf16 v[214:229], v[138:141], v[234:237], v[214:229]
	ds_read_b128 v[138:141], v143 offset:26624
	s_waitcnt lgkmcnt(3)
	v_mfma_f32_32x32x16_bf16 v[2:17], v[114:117], v[238:241], v[2:17]
	v_mfma_f32_32x32x16_bf16 v[18:33], v[114:117], v[246:249], v[18:33]
	s_waitcnt lgkmcnt(2)
	v_mfma_f32_32x32x16_bf16 v[34:49], v[118:121], v[238:241], v[34:49]
	v_mfma_f32_32x32x16_bf16 v[50:65], v[118:121], v[246:249], v[50:65]
	s_waitcnt lgkmcnt(1)
	v_mfma_f32_32x32x16_bf16 v[66:81], v[134:137], v[238:241], v[66:81]
	v_mfma_f32_32x32x16_bf16 v[82:97], v[134:137], v[246:249], v[82:97]
	s_waitcnt lgkmcnt(0)
	v_mfma_f32_32x32x16_bf16 v[98:113], v[138:141], v[238:241], v[98:113]
	v_mfma_f32_32x32x16_bf16 v[214:229], v[138:141], v[246:249], v[214:229]
	s_waitcnt vmcnt(6)
	s_barrier
	ds_read_b128 v[114:117], v142 offset:32768
	ds_read_b128 v[230:233], v144 offset:16512
	ds_read_b128 v[234:237], v144 offset:18560
	ds_read_b128 v[118:121], v142 offset:34816
	ds_read_b128 v[134:137], v142 offset:40960
	ds_read_b128 v[138:141], v142 offset:43008
	ds_read_b128 v[238:241], v145 offset:16512
	ds_read_b128 v[246:249], v145 offset:18560
	s_add_u32 m0, s18, 16384
	s_nop 0
	global_load_lds_dwordx4 v126, s[16:17]
	s_add_u32 m0, s18, 20480
	s_nop 0
	global_load_lds_dwordx4 v127, s[16:17]
	s_add_u32 m0, s18, 24576
	s_nop 0
	global_load_lds_dwordx4 v128, s[16:17]
	s_add_u32 m0, s18, 28672
	s_nop 0
	global_load_lds_dwordx4 v129, s[16:17]
	s_add_u32 m0, s18, 57344
	s_nop 0
	global_load_lds_dwordx4 v126, s[28:29]
	s_add_u32 m0, s18, 61440
	s_nop 0
	global_load_lds_dwordx4 v127, s[28:29]
	s_add_u32 s16, s16, 64
	s_addc_u32 s17, s17, 0
	s_add_u32 s28, s28, 64
	s_addc_u32 s29, s29, 0
	s_waitcnt lgkmcnt(6)
	v_mfma_f32_32x32x16_bf16 v[2:17], v[114:117], v[230:233], v[2:17]
	s_waitcnt lgkmcnt(5)
	v_mfma_f32_32x32x16_bf16 v[18:33], v[114:117], v[234:237], v[18:33]
	ds_read_b128 v[114:117], v143 offset:32768
	s_waitcnt lgkmcnt(5)
	v_mfma_f32_32x32x16_bf16 v[34:49], v[118:121], v[230:233], v[34:49]
	v_mfma_f32_32x32x16_bf16 v[50:65], v[118:121], v[234:237], v[50:65]
	ds_read_b128 v[118:121], v143 offset:34816
	s_waitcnt lgkmcnt(5)
	v_mfma_f32_32x32x16_bf16 v[66:81], v[134:137], v[230:233], v[66:81]
	v_mfma_f32_32x32x16_bf16 v[82:97], v[134:137], v[234:237], v[82:97]
	ds_read_b128 v[134:137], v143 offset:40960
	s_waitcnt lgkmcnt(5)
	v_mfma_f32_32x32x16_bf16 v[98:113], v[138:141], v[230:233], v[98:113]
	v_mfma_f32_32x32x16_bf16 v[214:229], v[138:141], v[234:237], v[214:229]
	ds_read_b128 v[138:141], v143 offset:43008
	s_waitcnt lgkmcnt(3)
	v_mfma_f32_32x32x16_bf16 v[2:17], v[114:117], v[238:241], v[2:17]
	v_mfma_f32_32x32x16_bf16 v[18:33], v[114:117], v[246:249], v[18:33]
	s_waitcnt lgkmcnt(2)
	v_mfma_f32_32x32x16_bf16 v[34:49], v[118:121], v[238:241], v[34:49]
	v_mfma_f32_32x32x16_bf16 v[50:65], v[118:121], v[246:249], v[50:65]
	s_waitcnt lgkmcnt(1)
	v_mfma_f32_32x32x16_bf16 v[66:81], v[134:137], v[238:241], v[66:81]
	v_mfma_f32_32x32x16_bf16 v[82:97], v[134:137], v[246:249], v[82:97]
	s_waitcnt lgkmcnt(0)
	v_mfma_f32_32x32x16_bf16 v[98:113], v[138:141], v[238:241], v[98:113]
	v_mfma_f32_32x32x16_bf16 v[214:229], v[138:141], v[246:249], v[214:229]
	s_branch .Lgu2_common
